# P7 sub-barriers: L1 invalidate issued together with the release write-back, before the spin
# speedup vs baseline: 1.0154x; 1.0034x over previous
; #define LAS __attribute__((address_space(3)))
; template <bool WITH_K>
; __device__ __forceinline__ void ret_load_qk(PR P, LAS bf16_t* QP, LAS bf16_t* KB, unsigned (&kth)[4][4], const int tidv, const int row0, const int n, const int h, const float kd0, const float g32) {
;     const bf16_t* PS = (const bf16_t*)(P.ws + WS_BIG); const float* rc = (const float*)(P.ws + WS_ROPE); const float* rs = rc + 2052 * 64;
;     float kd = kd0;
; #pragma unroll
;     for (int it = 0; it < 4; ++it) { const int idx = it * 512 + tidv, i = idx >> 4, f = (idx & 15) * 4;
;         const bf16_t* src = PS + (size_t)(row0 + i) * NCOLS + 1792 + h * 128;
;         const u32x2 q1 = *(const u32x2*)(src + f), q2 = *(const u32x2*)(src + 64 + f);
;         u32x2 k1 = (u32x2){0u, 0u}, k2 = k1; if (WITH_K) { k1 = *(const u32x2*)(src + 512 + f); k2 = *(const u32x2*)(src + 576 + f); }
;         const float4 cs = *(const float4*)(rc + (size_t)(n * 128 + i) * 64 + f), sn = *(const float4*)(rs + (size_t)(n * 128 + i) * 64 + f);
;         const float c4[4] = {cs.x, cs.y, cs.z, cs.w}, s4[4] = {sn.x, sn.y, sn.z, sn.w};
;         const float qa[4] = {lo_bf(q1.x), hi_bf(q1.x), lo_bf(q1.y), hi_bf(q1.y)}, qb[4] = {lo_bf(q2.x), hi_bf(q2.x), lo_bf(q2.y), hi_bf(q2.y)};
;         float qo1[4], qo2[4];
; #pragma unroll
;         for (int x = 0; x < 4; ++x) { qo1[x] = qa[x] * c4[x] - qb[x] * s4[x]; qo2[x] = qa[x] * s4[x] + qb[x] * c4[x]; }
;         u32x2 w; w.x = pg8::cvt_pk_bf16(qo1[0], qo1[1]); w.y = pg8::cvt_pk_bf16(qo1[2], qo1[3]); *(LAS u32x2*)(QP + i * RS + f) = w;
;         w.x = pg8::cvt_pk_bf16(qo2[0], qo2[1]); w.y = pg8::cvt_pk_bf16(qo2[2], qo2[3]); *(LAS u32x2*)(QP + i * RS + 64 + f) = w;
;         if (WITH_K) {
;             const float ka[4] = {lo_bf(k1.x), hi_bf(k1.x), lo_bf(k1.y), hi_bf(k1.y)}, kb[4] = {lo_bf(k2.x), hi_bf(k2.x), lo_bf(k2.y), hi_bf(k2.y)};
;             float ko1[4], ko2[4];
; #pragma unroll
;             for (int x = 0; x < 4; ++x) { ko1[x] = (ka[x] * c4[x] - kb[x] * s4[x]) * 0.08838834764831845f; ko2[x] = (ka[x] * s4[x] + kb[x] * c4[x]) * 0.08838834764831845f; }
;             w.x = pg8::cvt_pk_bf16(ko1[0], ko1[1]); w.y = pg8::cvt_pk_bf16(ko1[2], ko1[3]); *(LAS u32x2*)(KB + i * RS + f) = w;
;             w.x = pg8::cvt_pk_bf16(ko2[0], ko2[1]); w.y = pg8::cvt_pk_bf16(ko2[2], ko2[3]); *(LAS u32x2*)(KB + i * RS + 64 + f) = w;
.LBB0_618:
	s_add_i32 s8, s2, s55
	s_ashr_i32 s30, s8, 4
	s_and_b32 s12, s30, 3
	v_cvt_f32_ubyte0_e32 v0, s12
	v_sub_f32_e32 v0, 0xc0a00000, v0
	v_cmp_gt_f32_e32 vcc, s21, v0
	s_and_b64 s[8:9], vcc, exec
	s_cselect_b32 s8, 0xffffffc0, 0
	v_cndmask_b32_e32 v1, 0, v56, vcc
	v_add_f32_e32 v0, v0, v1
	v_exp_f32_e32 v0, v0
	v_mbcnt_lo_u32_b32 v11, -1, 0
	v_mbcnt_hi_u32_b32 v11, -1, v11
	s_nop 0
	v_add_u32_e32 v10, s33, v11
	v_ldexp_f32 v0, v0, s8
	v_sub_f32_e32 v52, 1.0, v0
	v_cmp_gt_f32_e32 vcc, s22, v52
	s_and_b64 s[8:9], vcc, exec
	s_cselect_b32 s31, 32, 0
	s_lshl_b32 s8, s30, 9
	s_and_b32 s8, s8, 0xfffff800
	v_ashrrev_i32_e32 v61, 4, v10
	s_or_b32 s29, s8, s6
	v_lshlrev_b32_e32 v0, 2, v11
	v_and_b32_e32 v60, 60, v0
	v_add_u32_e32 v0, s29, v61
	v_lshlrev_b32_e32 v28, 2, v60
	v_mad_i64_i32 v[0:1], s[8:9], v0, s23, v[30:31]
	s_lshl_b32 s12, s12, 8
	v_lshl_add_u64 v[6:7], s[14:15], 0, v[28:29]
	v_lshl_add_u64 v[4:5], s[16:17], 0, v[28:29]
	v_lshlrev_b32_e32 v28, 1, v60
	v_lshl_add_u64 v[0:1], v[0:1], 0, s[12:13]
	v_lshl_add_u64 v[2:3], v[0:1], 0, v[28:29]
	v_cndmask_b32_e32 v53, 0, v57, vcc
	v_add_co_u32_e32 v8, vcc, s24, v2
	s_nop 1
	v_addc_co_u32_e32 v9, vcc, 0, v3, vcc
	v_lshl_add_u64 v[2:3], v[2:3], 0, s[18:19]
	global_load_dwordx2 v[8:9], v[8:9], off offset:1536
	s_nop 0
	global_load_dwordx2 v[20:21], v[2:3], off offset:128
	global_load_dwordx2 v[24:25], v[2:3], off offset:1024
	global_load_dwordx2 v[26:27], v[2:3], off offset:1152
	v_add_u32_e32 v2, s6, v61
	v_ashrrev_i32_e32 v3, 31, v2
	v_lshlrev_b64 v[2:3], 8, v[2:3]
	v_lshl_add_u64 v[12:13], v[4:5], 0, v[2:3]
	v_lshl_add_u64 v[2:3], v[6:7], 0, v[2:3]
	global_load_dwordx4 v[12:15], v[12:13], off
	s_nop 0
	global_load_dwordx4 v[16:19], v[2:3], off
	v_add_u32_e32 v2, 0x200, v10
	v_ashrrev_i32_e32 v63, 4, v2
	v_add_u32_e32 v2, s6, v63
	v_ashrrev_i32_e32 v3, 31, v2
	v_lshlrev_b64 v[22:23], 8, v[2:3]
	v_add_u32_e32 v2, s29, v63
	v_mad_i64_i32 v[2:3], s[8:9], v2, s23, v[30:31]
	v_lshl_add_u64 v[2:3], v[2:3], 0, s[12:13]
	v_lshl_add_u64 v[34:35], v[2:3], 0, v[28:29]
	v_add_co_u32_e32 v36, vcc, s24, v34
	v_lshl_add_u64 v[32:33], v[6:7], 0, v[22:23]
	s_nop 0
	v_addc_co_u32_e32 v37, vcc, 0, v35, vcc
	v_lshl_add_u64 v[34:35], v[34:35], 0, s[18:19]
	global_load_dwordx2 v[44:45], v[36:37], off offset:1536
	global_load_dwordx2 v[46:47], v[34:35], off offset:128
	v_lshl_add_u64 v[22:23], v[4:5], 0, v[22:23]
	global_load_dwordx4 v[36:39], v[22:23], off
	global_load_dwordx4 v[40:43], v[32:33], off
	global_load_dwordx2 v[48:49], v[34:35], off offset:1024
	global_load_dwordx2 v[50:51], v[34:35], off offset:1152
	v_ldexp_f32 v22, v52, s31
	v_log_f32_e32 v22, v22
	v_mul_lo_u32 v23, v61, s25
	v_add3_u32 v72, 0, v23, v28
	v_sub_f32_e32 v62, v22, v53
	s_waitcnt vmcnt(0)
	v_lshlrev_b32_e32 v32, 16, v20
	v_lshlrev_b32_e32 v22, 16, v8
	v_and_b32_e32 v23, 0xffff0000, v8
	v_and_b32_e32 v33, 0xffff0000, v20
	v_lshlrev_b32_e32 v8, 16, v9
	v_and_b32_e32 v9, 0xffff0000, v9
	v_lshlrev_b32_e32 v20, 16, v21
	v_and_b32_e32 v21, 0xffff0000, v21
	v_pk_mul_f32 v[54:55], v[12:13], v[32:33]
	v_pk_mul_f32 v[64:65], v[12:13], v[22:23]
	v_pk_mul_f32 v[66:67], v[14:15], v[20:21]
	v_pk_mul_f32 v[68:69], v[14:15], v[8:9]
	v_lshlrev_b32_e32 v34, 16, v24
	v_and_b32_e32 v35, 0xffff0000, v24
	v_lshlrev_b32_e32 v52, 16, v26
	v_and_b32_e32 v53, 0xffff0000, v26
	v_pk_fma_f32 v[22:23], v[16:17], v[22:23], v[54:55] neg_lo:[0,0,1] neg_hi:[0,0,1]
	v_pk_fma_f32 v[32:33], v[16:17], v[32:33], v[64:65]
	v_pk_fma_f32 v[8:9], v[18:19], v[8:9], v[66:67] neg_lo:[0,0,1] neg_hi:[0,0,1]
	v_pk_fma_f32 v[20:21], v[18:19], v[20:21], v[68:69]
	v_pk_mul_f32 v[70:71], v[12:13], v[34:35]
	v_pk_mul_f32 v[12:13], v[12:13], v[52:53]
	v_cvt_pk_bf16_f32 v22, v22, v23
	v_cvt_pk_bf16_f32 v23, v8, v9
	v_cvt_pk_bf16_f32 v8, v32, v33
	v_cvt_pk_bf16_f32 v9, v20, v21
	ds_write2_b64 v72, v[22:23], v[8:9] offset1:16
	v_pk_fma_f32 v[8:9], v[16:17], v[34:35], v[12:13] neg_lo:[0,0,1] neg_hi:[0,0,1]
	v_pk_fma_f32 v[52:53], v[16:17], v[52:53], v[70:71]
	v_pk_mul_f32 v[22:23], v[8:9], s[20:21] op_sel_hi:[1,0]
	v_lshlrev_b32_e32 v8, 16, v25
	v_and_b32_e32 v9, 0xffff0000, v25
	v_lshlrev_b32_e32 v12, 16, v27
	v_and_b32_e32 v13, 0xffff0000, v27
	v_pk_mul_f32 v[16:17], v[14:15], v[8:9]
	v_pk_mul_f32 v[20:21], v[52:53], s[20:21] op_sel_hi:[1,0]
	v_pk_fma_f32 v[16:17], v[18:19], v[12:13], v[16:17]
	v_pk_mul_f32 v[12:13], v[14:15], v[12:13]
	v_pk_mul_f32 v[24:25], v[16:17], s[20:21] op_sel_hi:[1,0]
	v_pk_fma_f32 v[8:9], v[18:19], v[8:9], v[12:13] neg_lo:[0,0,1] neg_hi:[0,0,1]
	v_cvt_pk_bf16_f32 v12, v20, v21
	v_pk_mul_f32 v[26:27], v[8:9], s[20:21] op_sel_hi:[1,0]
	v_cvt_pk_bf16_f32 v8, v22, v23
	v_cvt_pk_bf16_f32 v9, v26, v27
	v_cvt_pk_bf16_f32 v13, v24, v25
	v_add_u32_e32 v14, 0x8800, v72
	ds_write2_b64 v14, v[8:9], v[12:13] offset1:16
	v_lshlrev_b32_e32 v12, 16, v46
	v_and_b32_e32 v13, 0xffff0000, v46
	v_lshlrev_b32_e32 v8, 16, v44
	v_and_b32_e32 v9, 0xffff0000, v44
	v_pk_mul_f32 v[14:15], v[36:37], v[12:13]
	v_lshlrev_b32_e32 v16, 16, v47
	v_pk_fma_f32 v[14:15], v[40:41], v[8:9], v[14:15] neg_lo:[0,0,1] neg_hi:[0,0,1]
	v_pk_mul_f32 v[8:9], v[36:37], v[8:9]
	v_and_b32_e32 v17, 0xffff0000, v47
	v_pk_fma_f32 v[8:9], v[40:41], v[12:13], v[8:9]
	v_lshlrev_b32_e32 v12, 16, v45
	v_and_b32_e32 v13, 0xffff0000, v45
	v_pk_mul_f32 v[18:19], v[38:39], v[16:17]
	v_cvt_pk_bf16_f32 v14, v14, v15
	v_pk_fma_f32 v[18:19], v[42:43], v[12:13], v[18:19] neg_lo:[0,0,1] neg_hi:[0,0,1]
	v_pk_mul_f32 v[12:13], v[38:39], v[12:13]
	v_cvt_pk_bf16_f32 v15, v18, v19
	v_pk_fma_f32 v[12:13], v[42:43], v[16:17], v[12:13]
	v_mul_lo_u32 v16, v63, s25
	v_add3_u32 v16, 0, v16, v28
	v_cvt_pk_bf16_f32 v8, v8, v9
; #define LAS __attribute__((address_space(3)))
; template <bool WITH_K>
; __device__ __forceinline__ void ret_load_qk(PR P, LAS bf16_t* QP, LAS bf16_t* KB, unsigned (&kth)[4][4], const int tidv, const int row0, const int n, const int h, const float kd0, const float g32) {
;     const bf16_t* PS = (const bf16_t*)(P.ws + WS_BIG); const float* rc = (const float*)(P.ws + WS_ROPE); const float* rs = rc + 2052 * 64;
;     float kd = kd0;
; #pragma unroll
;     for (int it = 0; it < 4; ++it) { const int idx = it * 512 + tidv, i = idx >> 4, f = (idx & 15) * 4;
;         const bf16_t* src = PS + (size_t)(row0 + i) * NCOLS + 1792 + h * 128;
;         const u32x2 q1 = *(const u32x2*)(src + f), q2 = *(const u32x2*)(src + 64 + f);
;         u32x2 k1 = (u32x2){0u, 0u}, k2 = k1; if (WITH_K) { k1 = *(const u32x2*)(src + 512 + f); k2 = *(const u32x2*)(src + 576 + f); }
;         const float4 cs = *(const float4*)(rc + (size_t)(n * 128 + i) * 64 + f), sn = *(const float4*)(rs + (size_t)(n * 128 + i) * 64 + f);
;         const float c4[4] = {cs.x, cs.y, cs.z, cs.w}, s4[4] = {sn.x, sn.y, sn.z, sn.w};
;         const float qa[4] = {lo_bf(q1.x), hi_bf(q1.x), lo_bf(q1.y), hi_bf(q1.y)}, qb[4] = {lo_bf(q2.x), hi_bf(q2.x), lo_bf(q2.y), hi_bf(q2.y)};
;         float qo1[4], qo2[4];
; #pragma unroll
;         for (int x = 0; x < 4; ++x) { qo1[x] = qa[x] * c4[x] - qb[x] * s4[x]; qo2[x] = qa[x] * s4[x] + qb[x] * c4[x]; }
;         u32x2 w; w.x = pg8::cvt_pk_bf16(qo1[0], qo1[1]); w.y = pg8::cvt_pk_bf16(qo1[2], qo1[3]); *(LAS u32x2*)(QP + i * RS + f) = w;
;         w.x = pg8::cvt_pk_bf16(qo2[0], qo2[1]); w.y = pg8::cvt_pk_bf16(qo2[2], qo2[3]); *(LAS u32x2*)(QP + i * RS + 64 + f) = w;
;         if (WITH_K) {
;             const float ka[4] = {lo_bf(k1.x), hi_bf(k1.x), lo_bf(k1.y), hi_bf(k1.y)}, kb[4] = {lo_bf(k2.x), hi_bf(k2.x), lo_bf(k2.y), hi_bf(k2.y)};
;             float ko1[4], ko2[4];
; #pragma unroll
;             for (int x = 0; x < 4; ++x) { ko1[x] = (ka[x] * c4[x] - kb[x] * s4[x]) * 0.08838834764831845f; ko2[x] = (ka[x] * s4[x] + kb[x] * c4[x]) * 0.08838834764831845f; }
;             w.x = pg8::cvt_pk_bf16(ko1[0], ko1[1]); w.y = pg8::cvt_pk_bf16(ko1[2], ko1[3]); *(LAS u32x2*)(KB + i * RS + f) = w;
;             w.x = pg8::cvt_pk_bf16(ko2[0], ko2[1]); w.y = pg8::cvt_pk_bf16(ko2[2], ko2[3]); *(LAS u32x2*)(KB + i * RS + 64 + f) = w;
	v_cvt_pk_bf16_f32 v9, v12, v13
	ds_write2_b64 v16, v[14:15], v[8:9] offset1:16
	v_lshlrev_b32_e32 v8, 16, v48
	v_and_b32_e32 v9, 0xffff0000, v48
	v_lshlrev_b32_e32 v12, 16, v50
	v_and_b32_e32 v13, 0xffff0000, v50
	v_pk_mul_f32 v[14:15], v[36:37], v[8:9]
	s_nop 0
	v_pk_fma_f32 v[14:15], v[40:41], v[12:13], v[14:15]
	v_pk_mul_f32 v[12:13], v[36:37], v[12:13]
	v_pk_mul_f32 v[32:33], v[14:15], s[20:21] op_sel_hi:[1,0]
	v_pk_fma_f32 v[8:9], v[40:41], v[8:9], v[12:13] neg_lo:[0,0,1] neg_hi:[0,0,1]
	v_lshlrev_b32_e32 v12, 16, v51
	v_pk_mul_f32 v[34:35], v[8:9], s[20:21] op_sel_hi:[1,0]
	v_lshlrev_b32_e32 v8, 16, v49
	v_and_b32_e32 v9, 0xffff0000, v49
	v_and_b32_e32 v13, 0xffff0000, v51
	v_pk_mul_f32 v[14:15], v[38:39], v[8:9]
	s_nop 0
	v_pk_fma_f32 v[14:15], v[42:43], v[12:13], v[14:15]
	v_pk_mul_f32 v[12:13], v[38:39], v[12:13]
	v_pk_mul_f32 v[36:37], v[14:15], s[20:21] op_sel_hi:[1,0]
	v_pk_fma_f32 v[8:9], v[42:43], v[8:9], v[12:13] neg_lo:[0,0,1] neg_hi:[0,0,1]
	v_cvt_pk_bf16_f32 v12, v32, v33
	v_pk_mul_f32 v[38:39], v[8:9], s[20:21] op_sel_hi:[1,0]
	v_cvt_pk_bf16_f32 v8, v34, v35
	v_cvt_pk_bf16_f32 v9, v38, v39
	v_cvt_pk_bf16_f32 v13, v36, v37
	v_add_u32_e32 v14, 0x8800, v16
	ds_write2_b64 v14, v[8:9], v[12:13] offset1:16
	v_add_u32_e32 v8, 0x400, v10
	v_ashrrev_i32_e32 v90, 4, v8
	v_add_u32_e32 v8, s29, v90
	v_mad_i64_i32 v[8:9], s[8:9], v8, s23, v[30:31]
	v_lshl_add_u64 v[8:9], v[8:9], 0, s[12:13]
	v_lshl_add_u64 v[12:13], v[8:9], 0, v[28:29]
	v_add_co_u32_e32 v14, vcc, s24, v12
	v_add_u32_e32 v48, 0x600, v10
	s_nop 0
	v_addc_co_u32_e32 v15, vcc, 0, v13, vcc
	v_lshl_add_u64 v[12:13], v[12:13], 0, s[18:19]
	global_load_dwordx2 v[40:41], v[14:15], off offset:1536
	global_load_dwordx2 v[42:43], v[12:13], off offset:128
	global_load_dwordx2 v[44:45], v[12:13], off offset:1024
	global_load_dwordx2 v[46:47], v[12:13], off offset:1152
	v_add_u32_e32 v12, s6, v90
	v_ashrrev_i32_e32 v13, 31, v12
	v_ashrrev_i32_e32 v91, 4, v48
	v_lshlrev_b64 v[16:17], 8, v[12:13]
	v_add_u32_e32 v49, s29, v91
	v_lshl_add_u64 v[12:13], v[4:5], 0, v[16:17]
	v_add_u32_e32 v48, s6, v91
	v_mad_i64_i32 v[50:51], s[8:9], v49, s23, v[30:31]
	global_load_dwordx4 v[12:15], v[12:13], off
	v_lshl_add_u64 v[16:17], v[6:7], 0, v[16:17]
	v_ashrrev_i32_e32 v49, 31, v48
	v_lshl_add_u64 v[64:65], v[50:51], 0, s[12:13]
	global_load_dwordx4 v[16:19], v[16:17], off
	v_lshlrev_b64 v[48:49], 8, v[48:49]
	v_lshl_add_u64 v[50:51], v[64:65], 0, v[28:29]
	v_lshl_add_u64 v[52:53], v[6:7], 0, v[48:49]
	v_add_co_u32_e32 v6, vcc, s24, v50
	v_lshl_add_u64 v[4:5], v[4:5], 0, v[48:49]
	s_nop 0
	v_addc_co_u32_e32 v7, vcc, 0, v51, vcc
	v_lshl_add_u64 v[50:51], v[50:51], 0, s[18:19]
	global_load_dwordx2 v[68:69], v[50:51], off offset:128
	global_load_dwordx2 v[66:67], v[6:7], off offset:1536
	s_nop 0
	global_load_dwordx4 v[4:7], v[4:5], off
	s_nop 0
	global_load_dwordx4 v[52:55], v[52:53], off
	s_nop 0
	global_load_dwordx2 v[70:71], v[50:51], off offset:1024
	global_load_dwordx2 v[72:73], v[50:51], off offset:1152
	v_mul_lo_u32 v48, v90, s25
	v_add3_u32 v92, 0, v48, v28
	s_waitcnt vmcnt(10)
	v_lshlrev_b32_e32 v50, 16, v42
	v_lshlrev_b32_e32 v48, 16, v40
	v_and_b32_e32 v49, 0xffff0000, v40
	v_and_b32_e32 v51, 0xffff0000, v42
	v_lshlrev_b32_e32 v40, 16, v41
	v_and_b32_e32 v41, 0xffff0000, v41
	v_lshlrev_b32_e32 v42, 16, v43
	v_and_b32_e32 v43, 0xffff0000, v43
	s_waitcnt vmcnt(9)
	v_lshlrev_b32_e32 v74, 16, v44
	v_and_b32_e32 v75, 0xffff0000, v44
	s_waitcnt vmcnt(8)
	v_lshlrev_b32_e32 v76, 16, v46
	v_and_b32_e32 v77, 0xffff0000, v46
	v_lshlrev_b32_e32 v44, 16, v45
	v_and_b32_e32 v45, 0xffff0000, v45
	v_lshlrev_b32_e32 v46, 16, v47
	v_and_b32_e32 v47, 0xffff0000, v47
	s_waitcnt vmcnt(7)
	v_pk_mul_f32 v[78:79], v[12:13], v[50:51]
	v_pk_mul_f32 v[80:81], v[12:13], v[48:49]
	v_pk_mul_f32 v[82:83], v[14:15], v[42:43]
	v_pk_mul_f32 v[84:85], v[14:15], v[40:41]
	v_pk_mul_f32 v[86:87], v[12:13], v[74:75]
	v_pk_mul_f32 v[12:13], v[12:13], v[76:77]
	v_pk_mul_f32 v[88:89], v[14:15], v[44:45]
	v_pk_mul_f32 v[14:15], v[14:15], v[46:47]
	s_waitcnt vmcnt(6)
	v_pk_fma_f32 v[48:49], v[16:17], v[48:49], v[78:79] neg_lo:[0,0,1] neg_hi:[0,0,1]
	v_pk_fma_f32 v[50:51], v[16:17], v[50:51], v[80:81]
	v_pk_fma_f32 v[40:41], v[18:19], v[40:41], v[82:83] neg_lo:[0,0,1] neg_hi:[0,0,1]
	v_pk_fma_f32 v[42:43], v[18:19], v[42:43], v[84:85]
	v_pk_fma_f32 v[76:77], v[16:17], v[76:77], v[86:87]
	v_pk_fma_f32 v[12:13], v[16:17], v[74:75], v[12:13] neg_lo:[0,0,1] neg_hi:[0,0,1]
	v_pk_fma_f32 v[16:17], v[18:19], v[46:47], v[88:89]
	v_pk_fma_f32 v[14:15], v[18:19], v[44:45], v[14:15] neg_lo:[0,0,1] neg_hi:[0,0,1]
	v_cvt_pk_bf16_f32 v18, v48, v49
	v_cvt_pk_bf16_f32 v19, v40, v41
	v_cvt_pk_bf16_f32 v49, v42, v43
	v_pk_mul_f32 v[40:41], v[76:77], s[20:21] op_sel_hi:[1,0]
	v_pk_mul_f32 v[44:45], v[12:13], s[20:21] op_sel_hi:[1,0]
	v_pk_mul_f32 v[42:43], v[16:17], s[20:21] op_sel_hi:[1,0]
	v_pk_mul_f32 v[46:47], v[14:15], s[20:21] op_sel_hi:[1,0]
	v_cvt_pk_bf16_f32 v12, v44, v45
	v_cvt_pk_bf16_f32 v13, v46, v47
	v_cvt_pk_bf16_f32 v14, v40, v41
	v_cvt_pk_bf16_f32 v15, v42, v43
	v_add_u32_e32 v16, 0x8800, v92
	ds_write2_b64 v16, v[12:13], v[14:15] offset1:16
	s_waitcnt vmcnt(5)
	v_lshlrev_b32_e32 v14, 16, v68
	v_and_b32_e32 v15, 0xffff0000, v68
	v_cvt_pk_bf16_f32 v48, v50, v51
	s_waitcnt vmcnt(4)
	v_lshlrev_b32_e32 v12, 16, v66
	v_and_b32_e32 v13, 0xffff0000, v66
	s_waitcnt vmcnt(3)
	v_pk_mul_f32 v[16:17], v[4:5], v[14:15]
	ds_write2_b64 v92, v[18:19], v[48:49] offset1:16
	s_waitcnt vmcnt(2)
; template <bool WITH_K>
; __device__ __forceinline__ void ret_load_qk(PR P, LAS bf16_t* QP, LAS bf16_t* KB, unsigned (&kth)[4][4], const int tidv, const int row0, const int n, const int h, const float kd0, const float g32) {
;     ...
;     for (int it = 0; it < 4; ++it) { const int idx = it * 512 + tidv, i = idx >> 4, f = (idx & 15) * 4;
;         const bf16_t* src = PS + (size_t)(row0 + i) * NCOLS + 1792 + h * 128;
;         const u32x2 q1 = *(const u32x2*)(src + f), q2 = *(const u32x2*)(src + 64 + f);
;         u32x2 k1 = (u32x2){0u, 0u}, k2 = k1; if (WITH_K) { k1 = *(const u32x2*)(src + 512 + f); k2 = *(const u32x2*)(src + 576 + f); }
;         const float4 cs = *(const float4*)(rc + (size_t)(n * 128 + i) * 64 + f), sn = *(const float4*)(rs + (size_t)(n * 128 + i) * 64 + f);
;         const float c4[4] = {cs.x, cs.y, cs.z, cs.w}, s4[4] = {sn.x, sn.y, sn.z, sn.w};
;         const float qa[4] = {lo_bf(q1.x), hi_bf(q1.x), lo_bf(q1.y), hi_bf(q1.y)}, qb[4] = {lo_bf(q2.x), hi_bf(q2.x), lo_bf(q2.y), hi_bf(q2.y)};
;         float qo1[4], qo2[4];
; #pragma unroll
;         for (int x = 0; x < 4; ++x) { qo1[x] = qa[x] * c4[x] - qb[x] * s4[x]; qo2[x] = qa[x] * s4[x] + qb[x] * c4[x]; }
;         u32x2 w; w.x = pg8::cvt_pk_bf16(qo1[0], qo1[1]); w.y = pg8::cvt_pk_bf16(qo1[2], qo1[3]); *(LAS u32x2*)(QP + i * RS + f) = w;
;         w.x = pg8::cvt_pk_bf16(qo2[0], qo2[1]); w.y = pg8::cvt_pk_bf16(qo2[2], qo2[3]); *(LAS u32x2*)(QP + i * RS + 64 + f) = w;
;         if (WITH_K) {
;             const float ka[4] = {lo_bf(k1.x), hi_bf(k1.x), lo_bf(k1.y), hi_bf(k1.y)}, kb[4] = {lo_bf(k2.x), hi_bf(k2.x), lo_bf(k2.y), hi_bf(k2.y)};
;             float ko1[4], ko2[4];
; #pragma unroll
;             for (int x = 0; x < 4; ++x) { ko1[x] = (ka[x] * c4[x] - kb[x] * s4[x]) * 0.08838834764831845f; ko2[x] = (ka[x] * s4[x] + kb[x] * c4[x]) * 0.08838834764831845f; }
;             w.x = pg8::cvt_pk_bf16(ko1[0], ko1[1]); w.y = pg8::cvt_pk_bf16(ko1[2], ko1[3]); *(LAS u32x2*)(KB + i * RS + f) = w;
;             w.x = pg8::cvt_pk_bf16(ko2[0], ko2[1]); w.y = pg8::cvt_pk_bf16(ko2[2], ko2[3]); *(LAS u32x2*)(KB + i * RS + 64 + f) = w;
;             kth[it][0] = pg8::cvt_pk_bf16(ko1[0] * kd, ko1[1] * kd); kth[it][1] = pg8::cvt_pk_bf16(ko1[2] * kd, ko1[3] * kd);
;             kth[it][2] = pg8::cvt_pk_bf16(ko2[0] * kd, ko2[1] * kd); kth[it][3] = pg8::cvt_pk_bf16(ko2[2] * kd, ko2[3] * kd); kd *= g32; }
	v_pk_fma_f32 v[16:17], v[52:53], v[12:13], v[16:17] neg_lo:[0,0,1] neg_hi:[0,0,1]
	v_pk_mul_f32 v[12:13], v[4:5], v[12:13]
	v_lshlrev_b32_e32 v18, 16, v69
	v_and_b32_e32 v19, 0xffff0000, v69
	v_pk_fma_f32 v[12:13], v[52:53], v[14:15], v[12:13]
	v_lshlrev_b32_e32 v14, 16, v67
	v_and_b32_e32 v15, 0xffff0000, v67
	v_pk_mul_f32 v[48:49], v[6:7], v[18:19]
	v_cvt_pk_bf16_f32 v16, v16, v17
	v_pk_fma_f32 v[48:49], v[54:55], v[14:15], v[48:49] neg_lo:[0,0,1] neg_hi:[0,0,1]
	v_pk_mul_f32 v[14:15], v[6:7], v[14:15]
	v_cvt_pk_bf16_f32 v17, v48, v49
	v_pk_fma_f32 v[14:15], v[54:55], v[18:19], v[14:15]
	v_mul_lo_u32 v18, v91, s25
	v_add3_u32 v18, 0, v18, v28
	v_cvt_pk_bf16_f32 v12, v12, v13
	v_cvt_pk_bf16_f32 v13, v14, v15
	ds_write2_b64 v18, v[16:17], v[12:13] offset1:16
	s_waitcnt vmcnt(1)
	v_lshlrev_b32_e32 v12, 16, v70
	v_and_b32_e32 v13, 0xffff0000, v70
	s_waitcnt vmcnt(0)
	v_lshlrev_b32_e32 v14, 16, v72
	v_and_b32_e32 v15, 0xffff0000, v72
	v_pk_mul_f32 v[16:17], v[4:5], v[12:13]
	v_pk_mul_f32 v[4:5], v[4:5], v[14:15]
	v_pk_fma_f32 v[16:17], v[52:53], v[14:15], v[16:17]
	v_pk_fma_f32 v[4:5], v[52:53], v[12:13], v[4:5] neg_lo:[0,0,1] neg_hi:[0,0,1]
	v_lshlrev_b32_e32 v12, 16, v73
	v_pk_mul_f32 v[50:51], v[4:5], s[20:21] op_sel_hi:[1,0]
	v_lshlrev_b32_e32 v4, 16, v71
	v_and_b32_e32 v5, 0xffff0000, v71
	v_and_b32_e32 v13, 0xffff0000, v73
	v_pk_mul_f32 v[14:15], v[6:7], v[4:5]
	v_pk_mul_f32 v[6:7], v[6:7], v[12:13]
	v_pk_fma_f32 v[14:15], v[54:55], v[12:13], v[14:15]
	v_pk_fma_f32 v[4:5], v[54:55], v[4:5], v[6:7] neg_lo:[0,0,1] neg_hi:[0,0,1]
	v_pk_mul_f32 v[48:49], v[16:17], s[20:21] op_sel_hi:[1,0]
	v_pk_mul_f32 v[52:53], v[14:15], s[20:21] op_sel_hi:[1,0]
	v_pk_mul_f32 v[54:55], v[4:5], s[20:21] op_sel_hi:[1,0]
	v_cvt_pk_bf16_f32 v4, v50, v51
	v_cvt_pk_bf16_f32 v5, v54, v55
	v_cvt_pk_bf16_f32 v6, v48, v49
	v_cvt_pk_bf16_f32 v7, v52, v53
	v_add_u32_e32 v12, 0x8800, v18
	ds_write2_b64 v12, v[4:5], v[6:7] offset1:16
	v_lshlrev_b32_e32 v4, 3, v11
	v_and_b32_e32 v66, 0x78, v4
	v_lshlrev_b32_e32 v28, 1, v66
	v_lshl_add_u64 v[0:1], v[0:1], 0, v[28:29]
	v_add_co_u32_e32 v0, vcc, s24, v0
	v_lshl_add_u64 v[8:9], v[8:9], 0, v[28:29]
	s_nop 0
	v_addc_co_u32_e32 v1, vcc, 0, v1, vcc
	global_load_dwordx4 v[4:7], v[0:1], off offset:3584
	v_lshl_add_u64 v[0:1], v[2:3], 0, v[28:29]
	v_add_co_u32_e32 v0, vcc, s24, v0
	v_lshlrev_b32_e32 v79, 1, v61
	s_nop 0
	v_addc_co_u32_e32 v1, vcc, 0, v1, vcc
	global_load_dwordx4 v[0:3], v[0:1], off offset:3584
	v_add_co_u32_e32 v8, vcc, s24, v8
	v_lshlrev_b32_e32 v78, 1, v63
	s_nop 0
	v_addc_co_u32_e32 v9, vcc, 0, v9, vcc
	global_load_dwordx4 v[12:15], v[8:9], off offset:3584
	v_lshl_add_u64 v[8:9], v[64:65], 0, v[28:29]
	v_add_co_u32_e32 v8, vcc, s24, v8
	v_bfe_u32 v28, v11, 4, 2
	s_nop 0
	v_addc_co_u32_e32 v9, vcc, 0, v9, vcc
	global_load_dwordx4 v[16:19], v[8:9], off offset:3584
	v_ashrrev_i32_e32 v9, 2, v10
	v_and_b32_e32 v8, 15, v11
	v_and_b32_e32 v69, 0xffffffe0, v9
	v_lshlrev_b32_e32 v75, 4, v28
	v_or_b32_e32 v11, v69, v8
	v_mad_u32_u24 v9, v66, s25, v58
	v_add_u32_e32 v73, 0, v75
	v_mul_lo_u32 v77, v11, s25
	v_lshlrev_b32_e32 v76, 1, v90
	v_lshlrev_b32_e32 v74, 1, v91
	v_add_u32_e32 v63, v9, v79
	v_add_u32_e32 v68, v73, v77
	v_add_u32_e32 v64, v9, v78
	v_add_u32_e32 v65, v9, v76
	v_add_u32_e32 v9, v9, v74
	s_waitcnt vmcnt(3)
	ds_write_b16 v63, v4
	ds_write_b16_d16_hi v63, v4 offset:272
	ds_write_b16 v63, v5 offset:544
	ds_write_b16_d16_hi v63, v5 offset:816
	ds_write_b16 v63, v6 offset:1088
	ds_write_b16_d16_hi v63, v6 offset:1360
	ds_write_b16 v63, v7 offset:1632
	ds_write_b16_d16_hi v63, v7 offset:1904
	s_waitcnt vmcnt(2)
	ds_write_b16 v64, v0
	ds_write_b16_d16_hi v64, v0 offset:272
	ds_write_b16 v64, v1 offset:544
	ds_write_b16_d16_hi v64, v1 offset:816
	ds_write_b16 v64, v2 offset:1088
	ds_write_b16_d16_hi v64, v2 offset:1360
	ds_write_b16 v64, v3 offset:1632
	ds_write_b16_d16_hi v64, v3 offset:1904
	s_waitcnt vmcnt(1)
	ds_write_b16 v65, v12
	ds_write_b16_d16_hi v65, v12 offset:272
	ds_write_b16 v65, v13 offset:544
	ds_write_b16_d16_hi v65, v13 offset:816
	ds_write_b16 v65, v14 offset:1088
	ds_write_b16_d16_hi v65, v14 offset:1360
	ds_write_b16 v65, v15 offset:1632
	ds_write_b16_d16_hi v65, v15 offset:1904
	s_waitcnt vmcnt(0)
	ds_write_b16 v9, v16
	ds_write_b16_d16_hi v9, v16 offset:272
	ds_write_b16 v9, v17 offset:544
	ds_write_b16_d16_hi v9, v17 offset:816
	ds_write_b16 v9, v18 offset:1088
	ds_write_b16_d16_hi v9, v18 offset:1360
	ds_write_b16 v9, v19 offset:1632
	ds_write_b16_d16_hi v9, v19 offset:1904
	s_waitcnt lgkmcnt(0)
	s_barrier
; #define LAS __attribute__((address_space(3)))
; __device__ __forceinline__ void ret_unit_a(PR P, LAS unsigned char* lds, const int bh, const int n, const int wv) {
;     ...
;     f32x4 accP[2][4];
; #pragma unroll
;     for (int mt = 0; mt < 2; ++mt)
; #pragma unroll
;         for (int nt = 0; nt < 4; ++nt) accP[mt][nt] = (f32x4){0.f, 0.f, 0.f, 0.f};
; #pragma unroll
;     for (int ks = 0; ks < 4; ++ks) { bf16x8 aq[2];
; #pragma unroll
;         for (int mt = 0; mt < 2; ++mt) aq[mt] = *(const LAS bf16x8*)(QP + (wr * 32 + mt * 16 + fr) * RS + ks * 32 + fq * 8);
; #pragma unroll
;         for (int nt = 0; nt < 4; ++nt) { const bf16x8 bk = *(const LAS bf16x8*)(KB + (wc * 64 + nt * 16 + fr) * RS + ks * 32 + fq * 8);
; #pragma unroll
;             for (int mt = 0; mt < 2; ++mt) accP[mt][nt] = __builtin_amdgcn_mfma_f32_16x16x32_bf16(aq[mt], bk, accP[mt][nt], 0, 0, 0); }
;         __builtin_amdgcn_sched_barrier(0); }
;     __syncthreads();
;     { float ri[2][4], cj[4];
; #pragma unroll
;       for (int mt = 0; mt < 2; ++mt)
; #pragma unroll
;           for (int j = 0; j < 4; ++j) ri[mt][j] = exp2f(lg2 * (float)(wr * 32 + mt * 16 + fq * 4 + j));
; #pragma unroll
;       for (int nt = 0; nt < 4; ++nt) cj[nt] = exp2f(-lg2 * (float)(wc * 64 + nt * 16 + fr));
	ds_read_b128 v[0:3], v68
	v_and_or_b32 v63, v10, 64, v8
	v_mad_u32_u24 v70, v63, s25, v73
	ds_read_b128 v[4:7], v68 offset:4352
	ds_read_b128 v[8:11], v70 offset:34816
	ds_read_b128 v[12:15], v70 offset:39168
	ds_read_b128 v[80:83], v70 offset:43520
	ds_read_b128 v[84:87], v70 offset:47872
	s_waitcnt lgkmcnt(3)
	v_mfma_f32_16x16x32_bf16 v[16:19], v[0:3], v[8:11], 0
	v_or_b32_e32 v116, 16, v63
	v_or_b32_e32 v117, 32, v63
	v_or_b32_e32 v118, 48, v63
	v_mfma_f32_16x16x32_bf16 v[8:11], v[4:7], v[8:11], 0
	s_waitcnt lgkmcnt(2)
	v_mfma_f32_16x16x32_bf16 v[64:67], v[0:3], v[12:15], 0
	v_mfma_f32_16x16x32_bf16 v[12:15], v[4:7], v[12:15], 0
	s_waitcnt lgkmcnt(1)
	v_mfma_f32_16x16x32_bf16 v[88:91], v[0:3], v[80:83], 0
	v_mfma_f32_16x16x32_bf16 v[80:83], v[4:7], v[80:83], 0
	s_waitcnt lgkmcnt(0)
	v_mfma_f32_16x16x32_bf16 v[0:3], v[0:3], v[84:87], 0
	v_mfma_f32_16x16x32_bf16 v[4:7], v[4:7], v[84:87], 0
	ds_read_b128 v[84:87], v68 offset:64
	ds_read_b128 v[92:95], v68 offset:4416
	ds_read_b128 v[96:99], v70 offset:34880
	ds_read_b128 v[100:103], v70 offset:39232
	s_waitcnt lgkmcnt(1)
	v_mfma_f32_16x16x32_bf16 v[16:19], v[84:87], v[96:99], v[16:19]
	v_mfma_f32_16x16x32_bf16 v[8:11], v[92:95], v[96:99], v[8:11]
	s_waitcnt lgkmcnt(0)
	v_mfma_f32_16x16x32_bf16 v[64:67], v[84:87], v[100:103], v[64:67]
	v_mfma_f32_16x16x32_bf16 v[12:15], v[92:95], v[100:103], v[12:15]
	ds_read_b128 v[96:99], v70 offset:43584
	ds_read_b128 v[100:103], v70 offset:47936
	s_waitcnt lgkmcnt(1)
	v_mfma_f32_16x16x32_bf16 v[88:91], v[84:87], v[96:99], v[88:91]
	v_mfma_f32_16x16x32_bf16 v[80:83], v[92:95], v[96:99], v[80:83]
	s_waitcnt lgkmcnt(0)
	v_mfma_f32_16x16x32_bf16 v[0:3], v[84:87], v[100:103], v[0:3]
	v_mfma_f32_16x16x32_bf16 v[4:7], v[92:95], v[100:103], v[4:7]
	ds_read_b128 v[84:87], v68 offset:128
	ds_read_b128 v[92:95], v68 offset:4480
	ds_read_b128 v[96:99], v70 offset:34944
	ds_read_b128 v[100:103], v70 offset:39296
	s_waitcnt lgkmcnt(1)
	v_mfma_f32_16x16x32_bf16 v[16:19], v[84:87], v[96:99], v[16:19]
	v_mfma_f32_16x16x32_bf16 v[8:11], v[92:95], v[96:99], v[8:11]
	s_waitcnt lgkmcnt(0)
	v_mfma_f32_16x16x32_bf16 v[64:67], v[84:87], v[100:103], v[64:67]
	v_mfma_f32_16x16x32_bf16 v[96:99], v[92:95], v[100:103], v[12:15]
	s_nop 2
	ds_read_b128 v[12:15], v70 offset:43648
	ds_read_b128 v[100:103], v70 offset:48000
	s_waitcnt lgkmcnt(1)
	v_mfma_f32_16x16x32_bf16 v[88:91], v[84:87], v[12:15], v[88:91]
	v_mfma_f32_16x16x32_bf16 v[80:83], v[92:95], v[12:15], v[80:83]
	s_waitcnt lgkmcnt(0)
	v_mfma_f32_16x16x32_bf16 v[0:3], v[84:87], v[100:103], v[0:3]
	v_mfma_f32_16x16x32_bf16 v[84:87], v[92:95], v[100:103], v[4:7]
	ds_read_b128 v[92:95], v68 offset:192
	ds_read_b128 v[100:103], v68 offset:4544
	s_nop 0
	ds_read_b128 v[4:7], v70 offset:35008
	ds_read_b128 v[104:107], v70 offset:39360
	s_waitcnt lgkmcnt(1)
	v_mfma_f32_16x16x32_bf16 v[108:111], v[92:95], v[4:7], v[16:19]
	v_mfma_f32_16x16x32_bf16 v[12:15], v[100:103], v[4:7], v[8:11]
	s_waitcnt lgkmcnt(0)
	v_mfma_f32_16x16x32_bf16 v[112:115], v[92:95], v[104:107], v[64:67]
	ds_read_b128 v[4:7], v70 offset:43712
	s_nop 1
	ds_read_b128 v[64:67], v70 offset:48064
	v_mfma_f32_16x16x32_bf16 v[8:11], v[100:103], v[104:107], v[96:99]
	s_waitcnt lgkmcnt(1)
	v_mfma_f32_16x16x32_bf16 v[88:91], v[92:95], v[4:7], v[88:91]
	v_mfma_f32_16x16x32_bf16 v[4:7], v[100:103], v[4:7], v[80:83]
	s_waitcnt lgkmcnt(0)
	v_mfma_f32_16x16x32_bf16 v[16:19], v[92:95], v[64:67], v[0:3]
	v_mfma_f32_16x16x32_bf16 v[0:3], v[100:103], v[64:67], v[84:87]
	v_lshl_or_b32 v72, v28, 2, v69
	v_cvt_f32_i32_e32 v28, v72
	v_or_b32_e32 v71, 1, v72
	v_cvt_f32_i32_e32 v65, v71
	v_or_b32_e32 v70, 2, v72
	v_mul_f32_e32 v64, v62, v28
	v_cmp_gt_f32_e32 vcc, s21, v64
	v_mul_f32_e32 v66, v62, v65
	v_or_b32_e32 v69, 3, v72
	v_cndmask_b32_e32 v64, 0, v56, vcc
	v_fmac_f32_e32 v64, v62, v28
	v_exp_f32_e32 v28, v64
	v_cndmask_b32_e32 v64, 0, v59, vcc
	v_cmp_gt_f32_e32 vcc, s21, v66
	v_or_b32_e32 v67, 16, v72
	v_ldexp_f32 v81, v28, v64
	v_cndmask_b32_e32 v66, 0, v56, vcc
	v_fmac_f32_e32 v66, v62, v65
	v_exp_f32_e32 v65, v66
	v_cvt_f32_i32_e32 v66, v70
	v_cndmask_b32_e32 v28, 0, v59, vcc
	v_cvt_f32_i32_e32 v64, v69
	v_ldexp_f32 v84, v65, v28
	v_mul_f32_e32 v28, v62, v66
	v_cmp_gt_f32_e32 vcc, s21, v28
	v_cvt_f32_i32_e32 v80, v67
	s_nop 0
	v_cndmask_b32_e32 v28, 0, v56, vcc
	v_fmac_f32_e32 v28, v62, v66
	v_mul_f32_e32 v66, v62, v64
	v_cndmask_b32_e32 v65, 0, v59, vcc
	v_cmp_gt_f32_e32 vcc, s21, v66
	v_exp_f32_e32 v28, v28
	s_barrier
; __device__ __forceinline__ bf16_t f2bf(float f) { unsigned u = __float_as_uint(f); u += 0x7FFFu + ((u >> 16) & 1u); return (bf16_t)(u >> 16); }
; __device__ __forceinline__ void ret_unit_a(PR P, LAS unsigned char* lds, const int bh, const int n, const int wv) {
;     ...
;           for (int j = 0; j < 4; ++j) ri[mt][j] = exp2f(lg2 * (float)(wr * 32 + mt * 16 + fq * 4 + j));
; #pragma unroll
;       for (int nt = 0; nt < 4; ++nt) cj[nt] = exp2f(-lg2 * (float)(wc * 64 + nt * 16 + fr));
; #pragma unroll
;       for (int mt = 0; mt < 2; ++mt)
; #pragma unroll
;           for (int nt = 0; nt < 4; ++nt)
; #pragma unroll
;               for (int j = 0; j < 4; ++j) { const int i = wr * 32 + mt * 16 + fq * 4 + j, jj = wc * 64 + nt * 16 + fr;
;                   const float val = i >= jj ? accP[mt][nt][j] * ri[mt][j] * cj[nt] : 0.f; QP[i * RS + jj] = f2bf(val); } }
	v_cndmask_b32_e32 v66, 0, v56, vcc
	v_fmac_f32_e32 v66, v62, v64
	v_exp_f32_e32 v64, v66
	v_ldexp_f32 v85, v28, v65
	v_cndmask_b32_e32 v28, 0, v59, vcc
	v_or_b32_e32 v66, 17, v72
	v_ldexp_f32 v86, v64, v28
	v_cvt_f32_i32_e32 v64, v66
	v_mul_f32_e32 v28, v62, v80
	v_cmp_gt_f32_e32 vcc, s21, v28
	v_mul_f32_e32 v65, v62, v64
	s_nop 0
	v_cndmask_b32_e32 v28, 0, v56, vcc
	v_fmac_f32_e32 v28, v62, v80
	v_cndmask_b32_e32 v80, 0, v59, vcc
	v_cmp_gt_f32_e32 vcc, s21, v65
	v_exp_f32_e32 v28, v28
	v_mul_f32_e32 v16, v81, v16
	v_cndmask_b32_e32 v65, 0, v56, vcc
	v_fmac_f32_e32 v65, v62, v64
	v_exp_f32_e32 v64, v65
	v_or_b32_e32 v65, 18, v72
	v_cvt_f32_i32_e32 v82, v65
	v_ldexp_f32 v87, v28, v80
	v_cndmask_b32_e32 v28, 0, v59, vcc
	v_ldexp_f32 v92, v64, v28
	v_or_b32_e32 v64, 19, v72
	v_cvt_f32_i32_e32 v80, v64
	v_mul_f32_e32 v28, v62, v82
	v_cmp_gt_f32_e32 vcc, s21, v28
	v_mul_f32_e32 v12, v87, v12
	v_mul_f32_e32 v8, v87, v8
	v_cndmask_b32_e32 v28, 0, v56, vcc
	v_fmac_f32_e32 v28, v62, v82
	v_mul_f32_e32 v82, v62, v80
	v_cmp_gt_f32_e64 s[8:9], s21, v82
	v_exp_f32_e32 v28, v28
	v_mul_f32_e32 v4, v87, v4
	v_cndmask_b32_e64 v82, 0, v56, s[8:9]
	v_fmac_f32_e32 v82, v62, v80
	v_exp_f32_e32 v80, v82
	v_cndmask_b32_e32 v82, 0, v59, vcc
	v_ldexp_f32 v93, v28, v82
	v_cndmask_b32_e64 v28, 0, v59, s[8:9]
	v_ldexp_f32 v94, v80, v28
	v_cvt_f32_ubyte0_e32 v28, v63
	v_mul_f32_e64 v80, -v62, v28
	v_cmp_gt_f32_e32 vcc, s21, v80
	v_mul_f32_e32 v0, v87, v0
	s_nop 0
	v_cndmask_b32_e32 v80, 0, v56, vcc
	v_fma_f32 v28, -v62, v28, v80
	v_cvt_f32_ubyte0_e32 v80, v116
	v_mul_f32_e64 v82, -v62, v80
	v_cmp_gt_f32_e64 s[8:9], s21, v82
	v_exp_f32_e32 v28, v28
	s_nop 0
	v_cndmask_b32_e64 v82, 0, v56, s[8:9]
	v_fma_f32 v80, -v62, v80, v82
	v_exp_f32_e32 v80, v80
	v_cndmask_b32_e32 v82, 0, v59, vcc
	v_ldexp_f32 v95, v28, v82
	v_cndmask_b32_e64 v28, 0, v59, s[8:9]
	v_ldexp_f32 v96, v80, v28
	v_cvt_f32_ubyte0_e32 v28, v117
	v_mul_f32_e64 v80, -v62, v28
	v_cmp_gt_f32_e32 vcc, s21, v80
	v_mul_f32_e32 v12, v95, v12
	v_mul_f32_e32 v8, v96, v8
	v_cndmask_b32_e32 v80, 0, v56, vcc
	v_fma_f32 v28, -v62, v28, v80
	v_cvt_f32_ubyte0_e32 v80, v118
	v_mul_f32_e64 v82, -v62, v80
	v_cmp_gt_f32_e64 s[8:9], s21, v82
	v_exp_f32_e32 v28, v28
	s_nop 0
	v_cndmask_b32_e64 v82, 0, v56, s[8:9]
	v_fma_f32 v80, -v62, v80, v82
	v_exp_f32_e32 v80, v80
	v_cndmask_b32_e32 v82, 0, v59, vcc
	v_ldexp_f32 v97, v28, v82
	v_mul_f32_e32 v82, v81, v108
	v_cndmask_b32_e64 v28, 0, v59, s[8:9]
	v_mul_f32_e32 v82, v95, v82
	v_cmp_lt_i32_e32 vcc, v72, v63
	v_ldexp_f32 v98, v80, v28
	v_lshlrev_b32_e32 v28, 1, v63
	v_cndmask_b32_e64 v82, v82, 0, vcc
	v_add_u32_e32 v80, 0, v28
	v_bfe_u32 v83, v82, 16, 1
	v_add3_u32 v99, v82, v83, s27
	v_mad_u64_u32 v[82:83], s[8:9], v72, s25, v[80:81]
	v_mul_f32_e32 v83, v84, v109
	v_mul_f32_e32 v83, v95, v83
	v_cmp_ge_i32_e64 s[8:9], v71, v63
	ds_write_b16_d16_hi v82, v99
	v_mul_f32_e32 v16, v98, v16
	v_cndmask_b32_e64 v83, 0, v83, s[8:9]
	v_bfe_u32 v99, v83, 16, 1
	v_add3_u32 v83, v83, v99, s27
	ds_write_b16_d16_hi v82, v83 offset:272
	v_mul_f32_e32 v83, v85, v110
	v_mul_f32_e32 v83, v95, v83
	v_cmp_ge_i32_e64 s[8:9], v70, v63
	v_cndmask_b32_e64 v8, v8, 0, vcc
	v_cmp_ge_i32_e32 vcc, v66, v116
	v_cndmask_b32_e64 v83, 0, v83, s[8:9]
	v_bfe_u32 v99, v83, 16, 1
	v_add3_u32 v83, v83, v99, s27
	ds_write_b16_d16_hi v82, v83 offset:544
	v_mul_f32_e32 v83, v86, v111
	v_mul_f32_e32 v83, v95, v83
	v_cmp_ge_i32_e64 s[8:9], v69, v63
	v_mul_f32_e32 v4, v97, v4
	v_mul_f32_e32 v0, v98, v0
	v_cndmask_b32_e64 v83, 0, v83, s[8:9]
	v_bfe_u32 v99, v83, 16, 1
	v_add3_u32 v83, v83, v99, s27
	ds_write_b16_d16_hi v82, v83 offset:816
	v_mul_f32_e32 v83, v81, v112
	v_mul_f32_e32 v83, v96, v83
	v_cmp_ge_i32_e64 s[8:9], v72, v116
	s_nop 1
	v_cndmask_b32_e64 v83, 0, v83, s[8:9]
	v_bfe_u32 v99, v83, 16, 1
	v_add3_u32 v83, v83, v99, s27
	ds_write_b16_d16_hi v82, v83 offset:32
	v_mul_f32_e32 v83, v84, v113
	v_mul_f32_e32 v83, v96, v83
	v_cmp_ge_i32_e64 s[8:9], v71, v116
	s_nop 1
	v_cndmask_b32_e64 v83, 0, v83, s[8:9]
	v_bfe_u32 v99, v83, 16, 1
	v_add3_u32 v83, v83, v99, s27
	ds_write_b16_d16_hi v82, v83 offset:304
	v_mul_f32_e32 v83, v85, v114
	v_mul_f32_e32 v83, v96, v83
	v_cmp_ge_i32_e64 s[8:9], v70, v116
	s_nop 1
	v_cndmask_b32_e64 v83, 0, v83, s[8:9]
	v_bfe_u32 v99, v83, 16, 1
	v_add3_u32 v83, v83, v99, s27
	ds_write_b16_d16_hi v82, v83 offset:576
	v_mul_f32_e32 v83, v86, v115
	v_mul_f32_e32 v83, v96, v83
	v_cmp_ge_i32_e64 s[8:9], v69, v116
	s_nop 1
	v_cndmask_b32_e64 v83, 0, v83, s[8:9]
	v_bfe_u32 v99, v83, 16, 1
	v_add3_u32 v83, v83, v99, s27
	ds_write_b16_d16_hi v82, v83 offset:848
	v_mul_f32_e32 v83, v81, v88
	v_mul_f32_e32 v83, v97, v83
	v_cmp_ge_i32_e64 s[8:9], v72, v117
	s_nop 1
	v_cndmask_b32_e64 v83, 0, v83, s[8:9]
	v_bfe_u32 v88, v83, 16, 1
	v_add3_u32 v83, v83, v88, s27
	ds_write_b16_d16_hi v82, v83 offset:64
	v_mul_f32_e32 v83, v84, v89
	v_mul_f32_e32 v83, v97, v83
	v_cmp_ge_i32_e64 s[8:9], v71, v117
	s_nop 1
	v_cndmask_b32_e64 v83, 0, v83, s[8:9]
	v_bfe_u32 v88, v83, 16, 1
	v_add3_u32 v83, v83, v88, s27
	ds_write_b16_d16_hi v82, v83 offset:336
	v_mul_f32_e32 v83, v85, v90
	v_mul_f32_e32 v83, v97, v83
	v_cmp_ge_i32_e64 s[8:9], v70, v117
	s_nop 1
	v_cndmask_b32_e64 v83, 0, v83, s[8:9]
	v_bfe_u32 v88, v83, 16, 1
	v_add3_u32 v83, v83, v88, s27
	ds_write_b16_d16_hi v82, v83 offset:608
	v_mul_f32_e32 v83, v86, v91
	v_mul_f32_e32 v83, v97, v83
	v_cmp_ge_i32_e64 s[8:9], v69, v117
	s_nop 1
	v_cndmask_b32_e64 v83, 0, v83, s[8:9]
	v_cmp_ge_i32_e64 s[8:9], v72, v118
	v_bfe_u32 v88, v83, 16, 1
	v_add3_u32 v83, v83, v88, s27
	v_cndmask_b32_e64 v16, 0, v16, s[8:9]
	v_bfe_u32 v81, v16, 16, 1
	v_add3_u32 v16, v16, v81, s27
; #define LAS __attribute__((address_space(3)))
; __device__ __forceinline__ bf16_t f2bf(float f) { unsigned u = __float_as_uint(f); u += 0x7FFFu + ((u >> 16) & 1u); return (bf16_t)(u >> 16); }
; __device__ __forceinline__ bf16_t* kvb_ptr(unsigned char* ws, int bh) { return (bf16_t*)(bh < 29 ? ws + WS_LA + (size_t)bh * 524288 : ws + WS_WIN + 17301504 + (size_t)(bh - 29) * 524288); }
; __device__ __forceinline__ void ret_unit_a(PR P, LAS unsigned char* lds, const int bh, const int n, const int wv) {
;     ...
;     const bf16_t* PS = (const bf16_t*)(P.ws + WS_BIG); bf16_t* Y = (bf16_t*)(P.ws + WS_XN); bf16_t* KVB = kvb_ptr(P.ws, bh) + (size_t)n * 16384;
;     const float lg2 = log2f(1.0f - exp2f(-5.0f - (float)h));
;     const float kd0 = exp2f(lg2 * (float)(127 - (tid >> 4))), g32 = exp2f(-32.0f * lg2);
;     ...
; #pragma unroll
;       for (int mt = 0; mt < 2; ++mt)
; #pragma unroll
;           for (int nt = 0; nt < 4; ++nt)
; #pragma unroll
;               for (int j = 0; j < 4; ++j) { const int i = wr * 32 + mt * 16 + fq * 4 + j, jj = wc * 64 + nt * 16 + fr;
;                   const float val = i >= jj ? accP[mt][nt][j] * ri[mt][j] * cj[nt] : 0.f; QP[i * RS + jj] = f2bf(val); } }
; #pragma unroll
;     for (int it = 0; it < 4; ++it) { const int idx = it * 512 + tid, j = idx >> 4, f = (idx & 15) * 4; LAS bf16_t* d = KB + f * RS + j;
;         d[0] = (bf16_t)(kth[it][0] & 0xffffu); d[RS] = (bf16_t)(kth[it][0] >> 16); d[2 * RS] = (bf16_t)(kth[it][1] & 0xffffu); d[3 * RS] = (bf16_t)(kth[it][1] >> 16);
;         LAS bf16_t* d2 = d + 64 * RS;
;         d2[0] = (bf16_t)(kth[it][2] & 0xffffu); d2[RS] = (bf16_t)(kth[it][2] >> 16); d2[2 * RS] = (bf16_t)(kth[it][3] & 0xffffu); d2[3 * RS] = (bf16_t)(kth[it][3] >> 16); }
	ds_write_b16_d16_hi v82, v16 offset:96
	v_mul_f32_e32 v16, v84, v17
	v_mul_f32_e32 v16, v98, v16
	v_cmp_ge_i32_e64 s[8:9], v71, v118
	ds_write_b16_d16_hi v82, v83 offset:880
	s_nop 0
	v_cndmask_b32_e64 v16, 0, v16, s[8:9]
	v_bfe_u32 v17, v16, 16, 1
	v_add3_u32 v16, v16, v17, s27
	ds_write_b16_d16_hi v82, v16 offset:368
	v_mul_f32_e32 v16, v85, v18
	v_mul_f32_e32 v16, v98, v16
	v_cmp_ge_i32_e64 s[8:9], v70, v118
	s_nop 1
	v_cndmask_b32_e64 v16, 0, v16, s[8:9]
	v_bfe_u32 v17, v16, 16, 1
	v_add3_u32 v16, v16, v17, s27
	ds_write_b16_d16_hi v82, v16 offset:640
	v_mul_f32_e32 v16, v86, v19
	v_mul_f32_e32 v16, v98, v16
	v_cmp_ge_i32_e64 s[8:9], v69, v118
	s_nop 1
	v_cndmask_b32_e64 v16, 0, v16, s[8:9]
	v_bfe_u32 v17, v16, 16, 1
	v_cmp_ge_i32_e64 s[8:9], v67, v63
	v_add3_u32 v16, v16, v17, s27
	ds_write_b16_d16_hi v82, v16 offset:912
	v_cndmask_b32_e64 v12, 0, v12, s[8:9]
	v_bfe_u32 v16, v12, 16, 1
	v_add3_u32 v12, v12, v16, s27
	v_mad_u64_u32 v[16:17], s[8:9], v67, s25, v[80:81]
	ds_write_b16_d16_hi v16, v12
	v_mul_f32_e32 v12, v92, v13
	v_mul_f32_e32 v12, v95, v12
	v_cmp_ge_i32_e64 s[8:9], v66, v63
	s_nop 1
	v_cndmask_b32_e64 v12, 0, v12, s[8:9]
	v_bfe_u32 v13, v12, 16, 1
	v_add3_u32 v12, v12, v13, s27
	ds_write_b16_d16_hi v16, v12 offset:272
	v_mul_f32_e32 v12, v93, v14
	v_mul_f32_e32 v12, v95, v12
	v_cmp_ge_i32_e64 s[8:9], v65, v63
	s_nop 1
	v_cndmask_b32_e64 v12, 0, v12, s[8:9]
	v_bfe_u32 v13, v12, 16, 1
	v_add3_u32 v12, v12, v13, s27
	ds_write_b16_d16_hi v16, v12 offset:544
	v_mul_f32_e32 v12, v94, v15
	v_mul_f32_e32 v12, v95, v12
	v_cmp_ge_i32_e64 s[8:9], v64, v63
	s_nop 1
	v_cndmask_b32_e64 v12, 0, v12, s[8:9]
	v_bfe_u32 v13, v12, 16, 1
	v_add3_u32 v12, v12, v13, s27
	ds_write_b16_d16_hi v16, v12 offset:816
	v_bfe_u32 v12, v8, 16, 1
	v_add3_u32 v8, v8, v12, s27
	ds_write_b16_d16_hi v16, v8 offset:32
	v_mul_f32_e32 v8, v92, v9
	v_mul_f32_e32 v8, v96, v8
	v_cndmask_b32_e32 v8, 0, v8, vcc
	v_bfe_u32 v9, v8, 16, 1
	v_add3_u32 v8, v8, v9, s27
	ds_write_b16_d16_hi v16, v8 offset:304
	v_mul_f32_e32 v8, v93, v10
	v_mul_f32_e32 v8, v96, v8
	v_cmp_ge_i32_e32 vcc, v65, v116
	s_ashr_i32 s9, s30, 31
	s_sub_i32 s8, s30, 29
	v_cndmask_b32_e32 v8, 0, v8, vcc
	v_bfe_u32 v9, v8, 16, 1
	v_add3_u32 v8, v8, v9, s27
	ds_write_b16_d16_hi v16, v8 offset:576
	v_mul_f32_e32 v8, v94, v11
	v_mul_f32_e32 v8, v96, v8
	v_cmp_ge_i32_e32 vcc, v64, v116
	s_cmp_lt_i32 s30, 29
	s_cselect_b32 s31, s28, 0x1444800
	v_cndmask_b32_e32 v8, 0, v8, vcc
	v_bfe_u32 v9, v8, 16, 1
	v_cmp_ge_i32_e32 vcc, v67, v117
	v_add3_u32 v8, v8, v9, s27
	ds_write_b16_d16_hi v16, v8 offset:848
	v_cndmask_b32_e32 v4, 0, v4, vcc
	v_bfe_u32 v8, v4, 16, 1
	v_add3_u32 v4, v4, v8, s27
	ds_write_b16_d16_hi v16, v4 offset:64
	v_mul_f32_e32 v4, v92, v5
	v_mul_f32_e32 v4, v97, v4
	v_cmp_ge_i32_e32 vcc, v66, v117
	s_cselect_b32 s8, s30, s8
	s_cselect_b32 s9, s9, 0
	v_cndmask_b32_e32 v4, 0, v4, vcc
	v_bfe_u32 v5, v4, 16, 1
	v_add3_u32 v4, v4, v5, s27
	ds_write_b16_d16_hi v16, v4 offset:336
	v_mul_f32_e32 v4, v93, v6
	v_mul_f32_e32 v4, v97, v4
	v_cmp_ge_i32_e32 vcc, v65, v117
	s_add_u32 s30, s10, s31
	s_addc_u32 s31, s11, 0
	v_cndmask_b32_e32 v4, 0, v4, vcc
	v_bfe_u32 v5, v4, 16, 1
	v_add3_u32 v4, v4, v5, s27
	ds_write_b16_d16_hi v16, v4 offset:608
	v_mul_f32_e32 v4, v94, v7
	v_mul_f32_e32 v4, v97, v4
	v_cmp_ge_i32_e32 vcc, v64, v117
	s_lshl_b64 s[8:9], s[8:9], 19
	s_add_u32 s8, s30, s8
	v_cndmask_b32_e32 v4, 0, v4, vcc
	v_bfe_u32 v5, v4, 16, 1
	v_cmp_ge_i32_e32 vcc, v67, v118
	v_add3_u32 v4, v4, v5, s27
	ds_write_b16_d16_hi v16, v4 offset:880
	v_cndmask_b32_e32 v0, 0, v0, vcc
	v_bfe_u32 v4, v0, 16, 1
	v_add3_u32 v0, v0, v4, s27
	ds_write_b16_d16_hi v16, v0 offset:96
	v_mul_f32_e32 v0, v92, v1
	v_mul_f32_e32 v0, v98, v0
	v_cmp_ge_i32_e32 vcc, v66, v118
	s_addc_u32 s9, s31, s9
	s_add_u32 s8, s8, s7
	v_cndmask_b32_e32 v0, 0, v0, vcc
	v_bfe_u32 v1, v0, 16, 1
	v_add3_u32 v0, v0, v1, s27
	ds_write_b16_d16_hi v16, v0 offset:368
	v_mul_f32_e32 v0, v93, v2
	v_mul_f32_e32 v0, v98, v0
	v_cmp_ge_i32_e32 vcc, v65, v118
	s_addc_u32 s9, s9, 0
	s_nop 0
	v_cndmask_b32_e32 v0, 0, v0, vcc
	v_bfe_u32 v1, v0, 16, 1
	v_add3_u32 v0, v0, v1, s27
	ds_write_b16_d16_hi v16, v0 offset:640
	v_mul_f32_e32 v0, v94, v3
	v_mul_f32_e32 v0, v98, v0
	v_cmp_ge_i32_e32 vcc, v64, v118
	s_nop 1
	v_cndmask_b32_e32 v4, 0, v0, vcc
	v_sub_u32_e32 v0, 0x7f, v61
	v_cvt_f32_i32_e32 v0, v0
	v_mul_f32_e32 v1, v62, v0
	v_cmp_gt_f32_e32 vcc, s21, v1
	s_nop 1
	v_cndmask_b32_e32 v1, 0, v56, vcc
	v_fmac_f32_e32 v1, v62, v0
	v_exp_f32_e32 v0, v1
	v_cndmask_b32_e32 v1, 0, v59, vcc
	v_ldexp_f32 v0, v0, v1
	v_pk_mul_f32 v[2:3], v[0:1], v[22:23] op_sel_hi:[0,1]
	v_cvt_pk_bf16_f32 v5, v2, v3
	v_pk_mul_f32 v[2:3], v[0:1], v[26:27] op_sel_hi:[0,1]
	v_cvt_pk_bf16_f32 v6, v2, v3
	v_pk_mul_f32 v[2:3], v[0:1], v[20:21] op_sel_hi:[0,1]
	v_cvt_pk_bf16_f32 v7, v2, v3
	v_pk_mul_f32 v[2:3], v[0:1], v[24:25] op_sel_hi:[0,1]
	v_mul_f32_e32 v1, 0xc2000000, v62
	v_cmp_gt_f32_e32 vcc, s21, v1
	s_and_b64 s[30:31], vcc, exec
	s_cselect_b32 s30, 0xffffffc0, 0
	v_cndmask_b32_e32 v1, 0, v56, vcc
	v_fmac_f32_e32 v1, 0xc2000000, v62
	v_exp_f32_e32 v1, v1
	v_cvt_pk_bf16_f32 v8, v2, v3
	v_ldexp_f32 v1, v1, s30
	v_mul_f32_e32 v0, v1, v0
	v_pk_mul_f32 v[2:3], v[0:1], v[34:35] op_sel_hi:[0,1]
	v_cvt_pk_bf16_f32 v9, v2, v3
	v_pk_mul_f32 v[2:3], v[0:1], v[38:39] op_sel_hi:[0,1]
	v_cvt_pk_bf16_f32 v10, v2, v3
	v_pk_mul_f32 v[2:3], v[0:1], v[32:33] op_sel_hi:[0,1]
	v_cvt_pk_bf16_f32 v11, v2, v3
	v_pk_mul_f32 v[2:3], v[0:1], v[36:37] op_sel_hi:[0,1]
	v_mul_f32_e32 v0, v1, v0
	v_cvt_pk_bf16_f32 v12, v2, v3
	v_pk_mul_f32 v[2:3], v[0:1], v[44:45] op_sel_hi:[0,1]
	v_cvt_pk_bf16_f32 v13, v2, v3
; #define LAS __attribute__((address_space(3)))
; __device__ __forceinline__ void ret_unit_a(PR P, LAS unsigned char* lds, const int bh, const int n, const int wv) {
;     ...
; #pragma unroll
;     for (int it = 0; it < 4; ++it) { const int idx = it * 512 + tid, j = idx >> 4, f = (idx & 15) * 4; LAS bf16_t* d = KB + f * RS + j;
;         d[0] = (bf16_t)(kth[it][0] & 0xffffu); d[RS] = (bf16_t)(kth[it][0] >> 16); d[2 * RS] = (bf16_t)(kth[it][1] & 0xffffu); d[3 * RS] = (bf16_t)(kth[it][1] >> 16);
;         LAS bf16_t* d2 = d + 64 * RS;
;         d2[0] = (bf16_t)(kth[it][2] & 0xffffu); d2[RS] = (bf16_t)(kth[it][2] >> 16); d2[2 * RS] = (bf16_t)(kth[it][3] & 0xffffu); d2[3 * RS] = (bf16_t)(kth[it][3] >> 16); }
;     __syncthreads();
;     f32x4 accY[2][4], accS[2][4];
; #pragma unroll
;     for (int mt = 0; mt < 2; ++mt)
; #pragma unroll
;         for (int nt = 0; nt < 4; ++nt) { accY[mt][nt] = (f32x4){0.f, 0.f, 0.f, 0.f}; accS[mt][nt] = (f32x4){0.f, 0.f, 0.f, 0.f}; }
; #pragma unroll
;     for (int ks = 0; ks < 4; ++ks) { bf16x8 ap[2], av[2];
; #pragma unroll
;         for (int mt = 0; mt < 2; ++mt) { ap[mt] = *(const LAS bf16x8*)(QP + (wr * 32 + mt * 16 + fr) * RS + ks * 32 + fq * 8); av[mt] = *(const LAS bf16x8*)(VT + (wr * 32 + mt * 16 + fr) * RS + ks * 32 + fq * 8); }
; #pragma unroll
;         for (int nt = 0; nt < 4; ++nt) { const bf16x8 bv = *(const LAS bf16x8*)(VT + (wc * 64 + nt * 16 + fr) * RS + ks * 32 + fq * 8), bkt = *(const LAS bf16x8*)(KB + (wc * 64 + nt * 16 + fr) * RS + ks * 32 + fq * 8);
; #pragma unroll
;             for (int mt = 0; mt < 2; ++mt) { accY[mt][nt] = __builtin_amdgcn_mfma_f32_16x16x32_bf16(ap[mt], bv, accY[mt][nt], 0, 0, 0); accS[mt][nt] = __builtin_amdgcn_mfma_f32_16x16x32_bf16(av[mt], bkt, accS[mt][nt], 0, 0, 0); } }
;         __builtin_amdgcn_sched_barrier(0); }
	v_pk_mul_f32 v[2:3], v[0:1], v[46:47] op_sel_hi:[0,1]
	v_cvt_pk_bf16_f32 v14, v2, v3
	v_pk_mul_f32 v[2:3], v[0:1], v[40:41] op_sel_hi:[0,1]
	v_cvt_pk_bf16_f32 v15, v2, v3
	v_pk_mul_f32 v[2:3], v[0:1], v[42:43] op_sel_hi:[0,1]
	v_mul_f32_e32 v0, v1, v0
	v_cvt_pk_bf16_f32 v17, v2, v3
	v_pk_mul_f32 v[2:3], v[0:1], v[50:51] op_sel_hi:[0,1]
	v_cvt_pk_bf16_f32 v18, v2, v3
	v_pk_mul_f32 v[2:3], v[0:1], v[54:55] op_sel_hi:[0,1]
	v_cvt_pk_bf16_f32 v19, v2, v3
	v_pk_mul_f32 v[2:3], v[0:1], v[48:49] op_sel_hi:[0,1]
	v_pk_mul_f32 v[0:1], v[0:1], v[52:53] op_sel_hi:[0,1]
	v_cvt_pk_bf16_f32 v0, v0, v1
	v_bfe_u32 v1, v4, 16, 1
	v_add3_u32 v1, v4, v1, s27
	ds_write_b16_d16_hi v16, v1 offset:912
	v_mad_u32_u24 v1, v60, s25, 0
	v_cvt_pk_bf16_f32 v2, v2, v3
	v_add_u32_e32 v3, v1, v79
	ds_write_b16 v3, v5 offset:34816
	ds_write_b16_d16_hi v3, v5 offset:35088
	ds_write_b16 v3, v6 offset:35360
	ds_write_b16_d16_hi v3, v6 offset:35632
	ds_write_b16 v3, v7 offset:52224
	ds_write_b16_d16_hi v3, v7 offset:52496
	ds_write_b16 v3, v8 offset:52768
	ds_write_b16_d16_hi v3, v8 offset:53040
	v_add_u32_e32 v3, v1, v78
	ds_write_b16 v3, v9 offset:34816
	ds_write_b16_d16_hi v3, v9 offset:35088
	ds_write_b16 v3, v10 offset:35360
	ds_write_b16_d16_hi v3, v10 offset:35632
	ds_write_b16 v3, v11 offset:52224
	ds_write_b16_d16_hi v3, v11 offset:52496
	ds_write_b16 v3, v12 offset:52768
	ds_write_b16_d16_hi v3, v12 offset:53040
	v_add_u32_e32 v3, v1, v76
	v_add_u32_e32 v1, v1, v74
	ds_write_b16 v3, v13 offset:34816
	ds_write_b16_d16_hi v3, v13 offset:35088
	ds_write_b16 v3, v14 offset:35360
	ds_write_b16_d16_hi v3, v14 offset:35632
	ds_write_b16 v3, v15 offset:52224
	ds_write_b16_d16_hi v3, v15 offset:52496
	ds_write_b16 v3, v17 offset:52768
	ds_write_b16_d16_hi v3, v17 offset:53040
	ds_write_b16 v1, v18 offset:34816
	ds_write_b16_d16_hi v1, v18 offset:35088
	ds_write_b16 v1, v19 offset:35360
	ds_write_b16_d16_hi v1, v19 offset:35632
	ds_write_b16 v1, v2 offset:52224
	ds_write_b16_d16_hi v1, v2 offset:52496
	ds_write_b16 v1, v0 offset:52768
	ds_write_b16_d16_hi v1, v0 offset:53040
	s_waitcnt lgkmcnt(0)
	s_barrier
	ds_read_b128 v[0:3], v68
	v_mul_u32_u24_e32 v5, 0x88, v63
	v_add_u32_e32 v4, s26, v75
	v_lshlrev_b32_e32 v16, 1, v5
	v_add_u32_e32 v61, v4, v16
	v_add_u32_e32 v62, v73, v16
	v_add_u32_e32 v60, v4, v77
	ds_read_b128 v[4:7], v61
	ds_read_b128 v[8:11], v60
	ds_read_b128 v[12:15], v68 offset:4352
	ds_read_b128 v[16:19], v61 offset:4352
	ds_read_b128 v[24:27], v62 offset:34816
	ds_read_b128 v[32:35], v60 offset:4352
	ds_read_b128 v[36:39], v62 offset:39168
	ds_read_b128 v[52:55], v61 offset:8704
	ds_read_b128 v[74:77], v61 offset:13056
	ds_read_b128 v[82:85], v62 offset:43520
	ds_read_b128 v[86:89], v62 offset:47872
	s_waitcnt lgkmcnt(10)
	v_mfma_f32_16x16x32_bf16 v[20:23], v[0:3], v[4:7], 0
	s_waitcnt lgkmcnt(6)
	v_mfma_f32_16x16x32_bf16 v[40:43], v[8:11], v[24:27], 0
	v_mfma_f32_16x16x32_bf16 v[4:7], v[12:15], v[4:7], 0
	s_waitcnt lgkmcnt(5)
	v_mfma_f32_16x16x32_bf16 v[24:27], v[32:35], v[24:27], 0
	v_mfma_f32_16x16x32_bf16 v[44:47], v[0:3], v[16:19], 0
	s_waitcnt lgkmcnt(4)
	v_mfma_f32_16x16x32_bf16 v[48:51], v[8:11], v[36:39], 0
	v_mfma_f32_16x16x32_bf16 v[16:19], v[12:15], v[16:19], 0
	v_mfma_f32_16x16x32_bf16 v[36:39], v[32:35], v[36:39], 0
	s_waitcnt lgkmcnt(3)
	v_mfma_f32_16x16x32_bf16 v[78:81], v[0:3], v[52:55], 0
	s_waitcnt lgkmcnt(1)
	v_mfma_f32_16x16x32_bf16 v[90:93], v[8:11], v[82:85], 0
	v_mfma_f32_16x16x32_bf16 v[52:55], v[12:15], v[52:55], 0
	v_mfma_f32_16x16x32_bf16 v[82:85], v[32:35], v[82:85], 0
	v_mfma_f32_16x16x32_bf16 v[0:3], v[0:3], v[74:77], 0
	s_waitcnt lgkmcnt(0)
	v_mfma_f32_16x16x32_bf16 v[8:11], v[8:11], v[86:89], 0
	v_mfma_f32_16x16x32_bf16 v[12:15], v[12:15], v[74:77], 0
	v_mfma_f32_16x16x32_bf16 v[32:35], v[32:35], v[86:89], 0
	ds_read_b128 v[74:77], v68 offset:64
	ds_read_b128 v[86:89], v61 offset:64
	ds_read_b128 v[94:97], v60 offset:64
	ds_read_b128 v[98:101], v68 offset:4416
	ds_read_b128 v[102:105], v61 offset:4416
	ds_read_b128 v[106:109], v62 offset:34880
	ds_read_b128 v[110:113], v60 offset:4416
	ds_read_b128 v[114:117], v62 offset:39232
	s_waitcnt lgkmcnt(6)
	v_mfma_f32_16x16x32_bf16 v[20:23], v[74:77], v[86:89], v[20:23]
	s_waitcnt lgkmcnt(2)
	v_mfma_f32_16x16x32_bf16 v[40:43], v[94:97], v[106:109], v[40:43]
	v_mfma_f32_16x16x32_bf16 v[4:7], v[98:101], v[86:89], v[4:7]
	s_waitcnt lgkmcnt(1)
	v_mfma_f32_16x16x32_bf16 v[24:27], v[110:113], v[106:109], v[24:27]
	v_mfma_f32_16x16x32_bf16 v[44:47], v[74:77], v[102:105], v[44:47]
	s_waitcnt lgkmcnt(0)
	v_mfma_f32_16x16x32_bf16 v[48:51], v[94:97], v[114:117], v[48:51]
	v_mfma_f32_16x16x32_bf16 v[16:19], v[98:101], v[102:105], v[16:19]
	ds_read_b128 v[86:89], v61 offset:8768
	ds_read_b128 v[102:105], v61 offset:13120
	v_mfma_f32_16x16x32_bf16 v[36:39], v[110:113], v[114:117], v[36:39]
	ds_read_b128 v[106:109], v62 offset:43584
	ds_read_b128 v[114:117], v62 offset:47936
	s_waitcnt lgkmcnt(3)
	v_mfma_f32_16x16x32_bf16 v[78:81], v[74:77], v[86:89], v[78:81]
	s_waitcnt lgkmcnt(1)
	v_mfma_f32_16x16x32_bf16 v[90:93], v[94:97], v[106:109], v[90:93]
	v_mfma_f32_16x16x32_bf16 v[52:55], v[98:101], v[86:89], v[52:55]
	v_mfma_f32_16x16x32_bf16 v[82:85], v[110:113], v[106:109], v[82:85]
	v_mfma_f32_16x16x32_bf16 v[0:3], v[74:77], v[102:105], v[0:3]
	s_waitcnt lgkmcnt(0)
	v_mfma_f32_16x16x32_bf16 v[8:11], v[94:97], v[114:117], v[8:11]
	v_mfma_f32_16x16x32_bf16 v[12:15], v[98:101], v[102:105], v[12:15]
	v_mfma_f32_16x16x32_bf16 v[32:35], v[110:113], v[114:117], v[32:35]
	ds_read_b128 v[74:77], v68 offset:128
	ds_read_b128 v[86:89], v61 offset:128
	ds_read_b128 v[94:97], v60 offset:128
	ds_read_b128 v[98:101], v68 offset:4480
	ds_read_b128 v[102:105], v61 offset:4480
	ds_read_b128 v[106:109], v62 offset:34944
	ds_read_b128 v[110:113], v60 offset:4480
	ds_read_b128 v[114:117], v62 offset:39296
	s_waitcnt lgkmcnt(6)
; #define LAS __attribute__((address_space(3)))
; __device__ __forceinline__ bf16_t f2bf(float f) { unsigned u = __float_as_uint(f); u += 0x7FFFu + ((u >> 16) & 1u); return (bf16_t)(u >> 16); }
; __device__ __forceinline__ void ret_unit_a(PR P, LAS unsigned char* lds, const int bh, const int n, const int wv) {
;     ...
;     for (int ks = 0; ks < 4; ++ks) { bf16x8 ap[2], av[2];
; #pragma unroll
;         for (int mt = 0; mt < 2; ++mt) { ap[mt] = *(const LAS bf16x8*)(QP + (wr * 32 + mt * 16 + fr) * RS + ks * 32 + fq * 8); av[mt] = *(const LAS bf16x8*)(VT + (wr * 32 + mt * 16 + fr) * RS + ks * 32 + fq * 8); }
; #pragma unroll
;         for (int nt = 0; nt < 4; ++nt) { const bf16x8 bv = *(const LAS bf16x8*)(VT + (wc * 64 + nt * 16 + fr) * RS + ks * 32 + fq * 8), bkt = *(const LAS bf16x8*)(KB + (wc * 64 + nt * 16 + fr) * RS + ks * 32 + fq * 8);
; #pragma unroll
;             for (int mt = 0; mt < 2; ++mt) { accY[mt][nt] = __builtin_amdgcn_mfma_f32_16x16x32_bf16(ap[mt], bv, accY[mt][nt], 0, 0, 0); accS[mt][nt] = __builtin_amdgcn_mfma_f32_16x16x32_bf16(av[mt], bkt, accS[mt][nt], 0, 0, 0); } }
;         __builtin_amdgcn_sched_barrier(0); }
; #pragma unroll
;     for (int mt = 0; mt < 2; ++mt)
; #pragma unroll
;         for (int nt = 0; nt < 4; ++nt)
; #pragma unroll
;             for (int j = 0; j < 4; ++j) { const int r = wr * 32 + mt * 16 + fq * 4 + j, c = wc * 64 + nt * 16 + fr;
;                 Y[(size_t)(row0 + r) * 1024 + 512 + h * 128 + c] = f2bf(accY[mt][nt][j]); KVB[r * 128 + c] = f2bf(accS[mt][nt][j]); }
	v_mfma_f32_16x16x32_bf16 v[20:23], v[74:77], v[86:89], v[20:23]
	s_waitcnt lgkmcnt(2)
	v_mfma_f32_16x16x32_bf16 v[40:43], v[94:97], v[106:109], v[40:43]
	v_mfma_f32_16x16x32_bf16 v[4:7], v[98:101], v[86:89], v[4:7]
	s_waitcnt lgkmcnt(1)
	v_mfma_f32_16x16x32_bf16 v[24:27], v[110:113], v[106:109], v[24:27]
	v_mfma_f32_16x16x32_bf16 v[44:47], v[74:77], v[102:105], v[44:47]
	s_waitcnt lgkmcnt(0)
	v_mfma_f32_16x16x32_bf16 v[48:51], v[94:97], v[114:117], v[48:51]
	v_mfma_f32_16x16x32_bf16 v[16:19], v[98:101], v[102:105], v[16:19]
	ds_read_b128 v[86:89], v61 offset:8832
	ds_read_b128 v[102:105], v61 offset:13184
	v_mfma_f32_16x16x32_bf16 v[36:39], v[110:113], v[114:117], v[36:39]
	ds_read_b128 v[106:109], v62 offset:43648
	ds_read_b128 v[114:117], v62 offset:48000
	s_waitcnt lgkmcnt(3)
	v_mfma_f32_16x16x32_bf16 v[78:81], v[74:77], v[86:89], v[78:81]
	s_waitcnt lgkmcnt(1)
	v_mfma_f32_16x16x32_bf16 v[90:93], v[94:97], v[106:109], v[90:93]
	v_mfma_f32_16x16x32_bf16 v[52:55], v[98:101], v[86:89], v[52:55]
	v_mfma_f32_16x16x32_bf16 v[82:85], v[110:113], v[106:109], v[82:85]
	v_mfma_f32_16x16x32_bf16 v[0:3], v[74:77], v[102:105], v[0:3]
	s_waitcnt lgkmcnt(0)
	v_mfma_f32_16x16x32_bf16 v[74:77], v[94:97], v[114:117], v[8:11]
	v_mfma_f32_16x16x32_bf16 v[86:89], v[98:101], v[102:105], v[12:15]
	v_mfma_f32_16x16x32_bf16 v[32:35], v[110:113], v[114:117], v[32:35]
	ds_read_b128 v[94:97], v68 offset:192
	ds_read_b128 v[8:11], v61 offset:192
	ds_read_b128 v[98:101], v60 offset:192
	ds_read_b128 v[102:105], v68 offset:4544
	ds_read_b128 v[12:15], v61 offset:4544
	s_waitcnt lgkmcnt(3)
	v_mfma_f32_16x16x32_bf16 v[106:109], v[94:97], v[8:11], v[20:23]
	s_nop 2
	ds_read_b128 v[20:23], v62 offset:35008
	ds_read_b128 v[110:113], v60 offset:4544
	ds_read_b128 v[114:117], v62 offset:39360
	s_waitcnt lgkmcnt(2)
	v_mfma_f32_16x16x32_bf16 v[40:43], v[98:101], v[20:23], v[40:43]
	v_mfma_f32_16x16x32_bf16 v[118:121], v[102:105], v[8:11], v[4:7]
	s_waitcnt lgkmcnt(1)
	v_mfma_f32_16x16x32_bf16 v[24:27], v[110:113], v[20:23], v[24:27]
	s_waitcnt lgkmcnt(0)
	v_mfma_f32_16x16x32_bf16 v[48:51], v[98:101], v[114:117], v[48:51]
	v_mfma_f32_16x16x32_bf16 v[20:23], v[102:105], v[12:15], v[16:19]
	v_mfma_f32_16x16x32_bf16 v[16:19], v[110:113], v[114:117], v[36:39]
	ds_read_b128 v[4:7], v61 offset:8896
	s_nop 1
	ds_read_b128 v[36:39], v61 offset:13248
	ds_read_b128 v[8:11], v62 offset:43712
	ds_read_b128 v[114:117], v62 offset:48064
	v_mfma_f32_16x16x32_bf16 v[44:47], v[94:97], v[12:15], v[44:47]
	s_waitcnt lgkmcnt(3)
	v_mfma_f32_16x16x32_bf16 v[78:81], v[94:97], v[4:7], v[78:81]
	s_waitcnt lgkmcnt(1)
	v_mfma_f32_16x16x32_bf16 v[90:93], v[98:101], v[8:11], v[90:93]
	v_mfma_f32_16x16x32_bf16 v[12:15], v[102:105], v[4:7], v[52:55]
	v_mfma_f32_16x16x32_bf16 v[8:11], v[110:113], v[8:11], v[82:85]
	v_mfma_f32_16x16x32_bf16 v[52:55], v[94:97], v[36:39], v[0:3]
	s_waitcnt lgkmcnt(0)
	v_mfma_f32_16x16x32_bf16 v[74:77], v[98:101], v[114:117], v[74:77]
	v_mfma_f32_16x16x32_bf16 v[4:7], v[102:105], v[36:39], v[86:89]
	v_mfma_f32_16x16x32_bf16 v[0:3], v[110:113], v[114:117], v[32:35]
	s_add_u32 s30, s4, s12
	s_nop 1
	v_add_u32_e32 v34, s29, v72
	s_addc_u32 s31, s5, 0
	v_ashrrev_i32_e32 v35, 31, v34
	v_lshl_add_u64 v[32:33], s[30:31], 0, v[28:29]
	v_bfe_u32 v28, v106, 16, 1
	v_lshlrev_b64 v[34:35], 11, v[34:35]
	v_lshlrev_b32_e32 v62, 7, v72
	v_add3_u32 v28, v106, v28, s27
	v_lshl_add_u64 v[34:35], v[32:33], 0, v[34:35]
	v_or_b32_e32 v36, v62, v63
	global_store_short_d16_hi v[34:35], v28, off
	v_bfe_u32 v28, v40, 16, 1
	v_ashrrev_i32_e32 v37, 31, v36
	v_add3_u32 v28, v40, v28, s27
	v_lshl_add_u64 v[38:39], v[36:37], 1, s[8:9]
	global_store_short_d16_hi v[38:39], v28, off
	v_add_u32_e32 v38, s29, v71
	v_ashrrev_i32_e32 v39, 31, v38
	v_bfe_u32 v28, v107, 16, 1
	v_lshlrev_b64 v[38:39], 11, v[38:39]
	v_add3_u32 v28, v107, v28, s27
	v_lshl_add_u64 v[38:39], v[32:33], 0, v[38:39]
	v_lshlrev_b32_e32 v82, 7, v71
	global_store_short_d16_hi v[38:39], v28, off
	v_bfe_u32 v28, v41, 16, 1
	v_or_b32_e32 v40, v82, v63
	v_add3_u32 v28, v41, v28, s27
	v_ashrrev_i32_e32 v41, 31, v40
	v_lshl_add_u64 v[60:61], v[40:41], 1, s[8:9]
	global_store_short_d16_hi v[60:61], v28, off
	v_add_u32_e32 v60, s29, v70
	v_ashrrev_i32_e32 v61, 31, v60
	v_bfe_u32 v28, v108, 16, 1
	v_lshlrev_b64 v[60:61], 11, v[60:61]
	v_lshlrev_b32_e32 v83, 7, v70
	v_add3_u32 v28, v108, v28, s27
	v_lshl_add_u64 v[60:61], v[32:33], 0, v[60:61]
	v_or_b32_e32 v70, v83, v63
	global_store_short_d16_hi v[60:61], v28, off
	v_bfe_u32 v28, v42, 16, 1
	v_ashrrev_i32_e32 v71, 31, v70
	v_add3_u32 v28, v42, v28, s27
	v_lshl_add_u64 v[72:73], v[70:71], 1, s[8:9]
	global_store_short_d16_hi v[72:73], v28, off
	v_add_u32_e32 v72, s29, v69
	v_ashrrev_i32_e32 v73, 31, v72
	v_bfe_u32 v28, v109, 16, 1
	v_lshlrev_b64 v[72:73], 11, v[72:73]
	v_add3_u32 v28, v109, v28, s27
	v_lshl_add_u64 v[72:73], v[32:33], 0, v[72:73]
	v_lshlrev_b32_e32 v84, 7, v69
	global_store_short_d16_hi v[72:73], v28, off
	v_bfe_u32 v28, v43, 16, 1
	v_or_b32_e32 v42, v84, v63
	v_add3_u32 v28, v43, v28, s27
	v_ashrrev_i32_e32 v43, 31, v42
	v_lshl_add_u64 v[68:69], v[42:43], 1, s[8:9]
	global_store_short_d16_hi v[68:69], v28, off
	v_bfe_u32 v28, v44, 16, 1
	v_add3_u32 v28, v44, v28, s27
	global_store_short_d16_hi v[34:35], v28, off offset:32
	v_bfe_u32 v28, v48, 16, 1
	v_ashrrev_i32_e32 v37, 31, v62
	v_add3_u32 v28, v48, v28, s27
	v_lshl_add_u64 v[36:37], v[36:37], 1, s[8:9]
	global_store_short_d16_hi v[36:37], v28, off offset:32
	v_bfe_u32 v28, v45, 16, 1
	v_add3_u32 v28, v45, v28, s27
	global_store_short_d16_hi v[38:39], v28, off offset:32
	v_bfe_u32 v28, v49, 16, 1
	v_ashrrev_i32_e32 v41, 31, v82
; __device__ __forceinline__ bf16_t f2bf(float f) { unsigned u = __float_as_uint(f); u += 0x7FFFu + ((u >> 16) & 1u); return (bf16_t)(u >> 16); }
; __device__ __forceinline__ void ret_unit_a(PR P, LAS unsigned char* lds, const int bh, const int n, const int wv) {
;     ...
; #pragma unroll
;     for (int mt = 0; mt < 2; ++mt)
; #pragma unroll
;         for (int nt = 0; nt < 4; ++nt)
; #pragma unroll
;             for (int j = 0; j < 4; ++j) { const int r = wr * 32 + mt * 16 + fq * 4 + j, c = wc * 64 + nt * 16 + fr;
;                 Y[(size_t)(row0 + r) * 1024 + 512 + h * 128 + c] = f2bf(accY[mt][nt][j]); KVB[r * 128 + c] = f2bf(accS[mt][nt][j]); }
	v_add3_u32 v28, v49, v28, s27
	v_lshl_add_u64 v[40:41], v[40:41], 1, s[8:9]
	global_store_short_d16_hi v[40:41], v28, off offset:32
	v_bfe_u32 v28, v46, 16, 1
	v_add3_u32 v28, v46, v28, s27
	global_store_short_d16_hi v[60:61], v28, off offset:32
	v_bfe_u32 v28, v50, 16, 1
	v_ashrrev_i32_e32 v71, 31, v83
	v_add3_u32 v28, v50, v28, s27
	v_lshl_add_u64 v[44:45], v[70:71], 1, s[8:9]
	global_store_short_d16_hi v[44:45], v28, off offset:32
	v_bfe_u32 v28, v47, 16, 1
	v_add3_u32 v28, v47, v28, s27
	global_store_short_d16_hi v[72:73], v28, off offset:32
	v_bfe_u32 v28, v51, 16, 1
	v_ashrrev_i32_e32 v43, 31, v84
	v_add3_u32 v28, v51, v28, s27
	v_lshl_add_u64 v[42:43], v[42:43], 1, s[8:9]
	global_store_short_d16_hi v[42:43], v28, off offset:32
	v_bfe_u32 v28, v78, 16, 1
	v_add3_u32 v28, v78, v28, s27
	global_store_short_d16_hi v[34:35], v28, off offset:64
	v_bfe_u32 v28, v90, 16, 1
	v_add3_u32 v28, v90, v28, s27
	global_store_short_d16_hi v[36:37], v28, off offset:64
	v_bfe_u32 v28, v79, 16, 1
	v_add3_u32 v28, v79, v28, s27
	global_store_short_d16_hi v[38:39], v28, off offset:64
	v_bfe_u32 v28, v91, 16, 1
	v_add3_u32 v28, v91, v28, s27
	global_store_short_d16_hi v[40:41], v28, off offset:64
	v_bfe_u32 v28, v80, 16, 1
	v_add3_u32 v28, v80, v28, s27
	global_store_short_d16_hi v[60:61], v28, off offset:64
	v_bfe_u32 v28, v92, 16, 1
	v_add3_u32 v28, v92, v28, s27
	global_store_short_d16_hi v[44:45], v28, off offset:64
	v_bfe_u32 v28, v81, 16, 1
	v_add3_u32 v28, v81, v28, s27
	global_store_short_d16_hi v[72:73], v28, off offset:64
	v_bfe_u32 v28, v93, 16, 1
	v_add3_u32 v28, v93, v28, s27
	global_store_short_d16_hi v[42:43], v28, off offset:64
	v_bfe_u32 v28, v52, 16, 1
	v_add3_u32 v28, v52, v28, s27
	global_store_short_d16_hi v[34:35], v28, off offset:96
	v_bfe_u32 v28, v74, 16, 1
	v_add3_u32 v28, v74, v28, s27
	global_store_short_d16_hi v[36:37], v28, off offset:96
	v_bfe_u32 v28, v53, 16, 1
	v_add3_u32 v28, v53, v28, s27
	global_store_short_d16_hi v[38:39], v28, off offset:96
	v_bfe_u32 v28, v75, 16, 1
	v_add3_u32 v28, v75, v28, s27
	global_store_short_d16_hi v[40:41], v28, off offset:96
	v_bfe_u32 v28, v54, 16, 1
	v_add3_u32 v28, v54, v28, s27
	global_store_short_d16_hi v[60:61], v28, off offset:96
	v_bfe_u32 v28, v76, 16, 1
	v_add3_u32 v28, v76, v28, s27
	global_store_short_d16_hi v[44:45], v28, off offset:96
	v_bfe_u32 v28, v55, 16, 1
	v_add3_u32 v28, v55, v28, s27
	global_store_short_d16_hi v[72:73], v28, off offset:96
	v_bfe_u32 v28, v77, 16, 1
	v_add_u32_e32 v34, s29, v67
	v_add3_u32 v28, v77, v28, s27
	v_ashrrev_i32_e32 v35, 31, v34
	global_store_short_d16_hi v[42:43], v28, off offset:96
	v_bfe_u32 v28, v118, 16, 1
	v_lshlrev_b64 v[34:35], 11, v[34:35]
	v_add3_u32 v28, v118, v28, s27
	v_lshl_add_u64 v[34:35], v[32:33], 0, v[34:35]
	global_store_short_d16_hi v[34:35], v28, off
	v_bfe_u32 v28, v24, 16, 1
	v_add3_u32 v24, v24, v28, s27
	v_lshlrev_b32_e32 v28, 7, v67
	v_or_b32_e32 v36, v28, v63
	v_ashrrev_i32_e32 v37, 31, v36
	v_lshl_add_u64 v[38:39], v[36:37], 1, s[8:9]
	global_store_short_d16_hi v[38:39], v24, off
	v_add_u32_e32 v38, s29, v66
	v_ashrrev_i32_e32 v39, 31, v38
	v_bfe_u32 v24, v119, 16, 1
	v_lshlrev_b64 v[38:39], 11, v[38:39]
	v_add3_u32 v24, v119, v24, s27
	v_lshl_add_u64 v[38:39], v[32:33], 0, v[38:39]
	global_store_short_d16_hi v[38:39], v24, off
	v_bfe_u32 v24, v25, 16, 1
	v_lshlrev_b32_e32 v46, 7, v66
	v_add3_u32 v37, v25, v24, s27
	v_or_b32_e32 v24, v46, v63
	v_ashrrev_i32_e32 v25, 31, v24
	v_lshl_add_u64 v[40:41], v[24:25], 1, s[8:9]
	global_store_short_d16_hi v[40:41], v37, off
	v_add_u32_e32 v40, s29, v65
	v_ashrrev_i32_e32 v41, 31, v40
	v_bfe_u32 v25, v120, 16, 1
	v_lshlrev_b64 v[40:41], 11, v[40:41]
	v_lshlrev_b32_e32 v47, 7, v65
	v_add3_u32 v25, v120, v25, s27
	v_lshl_add_u64 v[40:41], v[32:33], 0, v[40:41]
	v_or_b32_e32 v42, v47, v63
	global_store_short_d16_hi v[40:41], v25, off
	v_bfe_u32 v25, v26, 16, 1
	v_ashrrev_i32_e32 v43, 31, v42
	v_add3_u32 v25, v26, v25, s27
	v_lshl_add_u64 v[44:45], v[42:43], 1, s[8:9]
	global_store_short_d16_hi v[44:45], v25, off
	v_add_u32_e32 v44, s29, v64
	v_ashrrev_i32_e32 v45, 31, v44
; __device__ __forceinline__ int fresh_tid(int wv) { int l; asm volatile("v_mbcnt_lo_u32_b32 %0, -1, 0\n\tv_mbcnt_hi_u32_b32 %0, -1, %0" : "=v"(l)); return wv * 64 + l; }
; __device__ __forceinline__ bf16_t f2bf(float f) { unsigned u = __float_as_uint(f); u += 0x7FFFu + ((u >> 16) & 1u); return (bf16_t)(u >> 16); }
; __device__ __forceinline__ unsigned xb_add(unsigned* p, unsigned v) { return __hip_atomic_fetch_add(p, v, __ATOMIC_RELAXED, __HIP_MEMORY_SCOPE_AGENT); }
; __device__ __forceinline__ void ret_unit_a(PR P, LAS unsigned char* lds, const int bh, const int n, const int wv) {
;     ...
; #pragma unroll
;     for (int mt = 0; mt < 2; ++mt)
; #pragma unroll
;         for (int nt = 0; nt < 4; ++nt)
; #pragma unroll
;             for (int j = 0; j < 4; ++j) { const int r = wr * 32 + mt * 16 + fq * 4 + j, c = wc * 64 + nt * 16 + fr;
;                 Y[(size_t)(row0 + r) * 1024 + 512 + h * 128 + c] = f2bf(accY[mt][nt][j]); KVB[r * 128 + c] = f2bf(accS[mt][nt][j]); }
; __device__ __forceinline__ void sub_barrier(unsigned* cnt, const unsigned target, const int wv) {
;     asm volatile("s_waitcnt vmcnt(0)" ::: "memory");
;     __syncthreads();
;     if (fresh_tid(wv) == 0) {
;         __builtin_amdgcn_fence(__ATOMIC_RELEASE, "agent");
;         asm volatile("s_waitcnt vmcnt(0)" ::: "memory");
;         (void)xb_add(cnt, 1u);
	v_bfe_u32 v25, v121, 16, 1
	v_lshlrev_b64 v[44:45], 11, v[44:45]
	v_add3_u32 v25, v121, v25, s27
	v_lshl_add_u64 v[32:33], v[32:33], 0, v[44:45]
	v_lshlrev_b32_e32 v48, 7, v64
	global_store_short_d16_hi v[32:33], v25, off
	v_bfe_u32 v25, v27, 16, 1
	v_or_b32_e32 v26, v48, v63
	v_add3_u32 v25, v27, v25, s27
	v_ashrrev_i32_e32 v27, 31, v26
	v_lshl_add_u64 v[44:45], v[26:27], 1, s[8:9]
	global_store_short_d16_hi v[44:45], v25, off
	v_bfe_u32 v25, v20, 16, 1
	v_add3_u32 v20, v20, v25, s27
	global_store_short_d16_hi v[34:35], v20, off offset:32
	v_bfe_u32 v20, v16, 16, 1
	v_ashrrev_i32_e32 v37, 31, v28
	v_add3_u32 v16, v16, v20, s27
	v_lshl_add_u64 v[36:37], v[36:37], 1, s[8:9]
	global_store_short_d16_hi v[36:37], v16, off offset:32
	v_bfe_u32 v16, v21, 16, 1
	v_add3_u32 v16, v21, v16, s27
	global_store_short_d16_hi v[38:39], v16, off offset:32
	v_bfe_u32 v16, v17, 16, 1
	v_ashrrev_i32_e32 v25, 31, v46
	v_add3_u32 v20, v17, v16, s27
	v_lshl_add_u64 v[16:17], v[24:25], 1, s[8:9]
	global_store_short_d16_hi v[16:17], v20, off offset:32
	v_bfe_u32 v20, v22, 16, 1
	v_add3_u32 v20, v22, v20, s27
	global_store_short_d16_hi v[40:41], v20, off offset:32
	v_bfe_u32 v20, v18, 16, 1
	v_ashrrev_i32_e32 v43, 31, v47
	v_add3_u32 v18, v18, v20, s27
	v_lshl_add_u64 v[20:21], v[42:43], 1, s[8:9]
	global_store_short_d16_hi v[20:21], v18, off offset:32
	v_bfe_u32 v18, v23, 16, 1
	v_add3_u32 v18, v23, v18, s27
	global_store_short_d16_hi v[32:33], v18, off offset:32
	v_bfe_u32 v18, v19, 16, 1
	v_ashrrev_i32_e32 v27, 31, v48
	v_add3_u32 v22, v19, v18, s27
	v_lshl_add_u64 v[18:19], v[26:27], 1, s[8:9]
	global_store_short_d16_hi v[18:19], v22, off offset:32
	v_bfe_u32 v22, v12, 16, 1
	v_add3_u32 v12, v12, v22, s27
	global_store_short_d16_hi v[34:35], v12, off offset:64
	v_bfe_u32 v12, v8, 16, 1
	v_add3_u32 v8, v8, v12, s27
	global_store_short_d16_hi v[36:37], v8, off offset:64
	v_bfe_u32 v8, v13, 16, 1
	v_add3_u32 v8, v13, v8, s27
	global_store_short_d16_hi v[38:39], v8, off offset:64
	v_bfe_u32 v8, v9, 16, 1
	v_add3_u32 v8, v9, v8, s27
	global_store_short_d16_hi v[16:17], v8, off offset:64
	v_bfe_u32 v8, v14, 16, 1
	v_add3_u32 v8, v14, v8, s27
	global_store_short_d16_hi v[40:41], v8, off offset:64
	v_bfe_u32 v8, v10, 16, 1
	v_add3_u32 v8, v10, v8, s27
	global_store_short_d16_hi v[20:21], v8, off offset:64
	v_bfe_u32 v8, v15, 16, 1
	v_add3_u32 v8, v15, v8, s27
	global_store_short_d16_hi v[32:33], v8, off offset:64
	v_bfe_u32 v8, v11, 16, 1
	v_add3_u32 v8, v11, v8, s27
	global_store_short_d16_hi v[18:19], v8, off offset:64
	v_bfe_u32 v8, v4, 16, 1
	v_add3_u32 v4, v4, v8, s27
	global_store_short_d16_hi v[34:35], v4, off offset:96
	v_bfe_u32 v4, v0, 16, 1
	v_add3_u32 v0, v0, v4, s27
	global_store_short_d16_hi v[36:37], v0, off offset:96
	v_bfe_u32 v0, v5, 16, 1
	v_add3_u32 v0, v5, v0, s27
	global_store_short_d16_hi v[38:39], v0, off offset:96
	v_bfe_u32 v0, v1, 16, 1
	v_add3_u32 v0, v1, v0, s27
	global_store_short_d16_hi v[16:17], v0, off offset:96
	v_bfe_u32 v0, v6, 16, 1
	v_add3_u32 v0, v6, v0, s27
	global_store_short_d16_hi v[40:41], v0, off offset:96
	v_bfe_u32 v0, v2, 16, 1
	v_add3_u32 v0, v2, v0, s27
	global_store_short_d16_hi v[20:21], v0, off offset:96
	v_bfe_u32 v0, v7, 16, 1
	v_add3_u32 v0, v7, v0, s27
	global_store_short_d16_hi v[32:33], v0, off offset:96
	v_bfe_u32 v0, v3, 16, 1
	s_addk_i32 s55, 0x80
	v_add3_u32 v0, v3, v0, s27
	s_cmpk_eq_i32 s55, 0x180
	global_store_short_d16_hi v[18:19], v0, off offset:96
	s_waitcnt vmcnt(63) expcnt(7) lgkmcnt(15)
	s_barrier
	s_cbranch_scc0 .LBB0_618
	s_waitcnt vmcnt(0)
	s_add_u32 s12, s10, 0x3700
	s_addc_u32 s13, s11, 0
	s_barrier
	v_mbcnt_lo_u32_b32 v0, -1, 0
	v_mbcnt_hi_u32_b32 v0, -1, v0
	s_nop 0
	v_cmp_eq_u32_e32 vcc, s74, v0
	s_and_saveexec_b64 s[8:9], vcc
	s_cbranch_execz .LBB0_636
	s_mov_b64 s[18:19], exec
	buffer_wbl2 sc1
	buffer_inv sc1
	s_waitcnt vmcnt(0)
	s_waitcnt vmcnt(0)
	v_mbcnt_lo_u32_b32 v0, s18, 0
	v_mbcnt_hi_u32_b32 v0, s19, v0
	v_cmp_eq_u32_e32 vcc, 0, v0
	s_and_saveexec_b64 s[20:21], vcc
	s_cbranch_execz .LBB0_622
	s_bcnt1_i32_b64 s18, s[18:19]
	v_mov_b32_e32 v0, 0
	v_mov_b32_e32 v1, s18
	global_atomic_add v0, v1, s[12:13]

; __device__ __forceinline__ unsigned cvt_pk_bf16(float lo, float hi) { const f32x2_t v = {lo, hi}; const bf16x2_t b = __builtin_convertvector(v, bf16x2_t); return __builtin_bit_cast(unsigned, b); }
; __device__ __forceinline__ float lo_bf(unsigned x) { return __uint_as_float(x << 16); }
; __device__ __forceinline__ float hi_bf(unsigned x) { return __uint_as_float(x & 0xffff0000u); }
; __device__ __forceinline__ unsigned xb_ld(unsigned* p)              { return __hip_atomic_load(p, __ATOMIC_RELAXED, __HIP_MEMORY_SCOPE_AGENT); }
; __device__ __forceinline__ bf16_t* kvb_ptr(unsigned char* ws, int bh) { return (bf16_t*)(bh < 29 ? ws + WS_LA + (size_t)bh * 524288 : ws + WS_WIN + 17301504 + (size_t)(bh - 29) * 524288); }
; __device__ __forceinline__ void ret_prefix(PR P, const int item) {
;     const int bh = item >> 11, i8 = (item & 2047) * 8; const int h = bh & 3;
;     bf16_t* KVB = kvb_ptr(P.ws, bh) + i8;
;     const float lg2 = log2f(1.0f - exp2f(-5.0f - (float)h)); const float c_dec = exp2f(lg2 * 128.0f);
;     u32x4 kv[16];
; #pragma unroll
;     for (int n = 0; n < 16; ++n) kv[n] = *(const u32x4*)(KVB + (size_t)n * 16384);
;     float S[8];
; #pragma unroll
;     for (int x = 0; x < 8; ++x) S[x] = 0.f;
; #pragma unroll
;     for (int n = 0; n < 16; ++n) { u32x4 w; w.x = pg8::cvt_pk_bf16(S[0], S[1]); w.y = pg8::cvt_pk_bf16(S[2], S[3]); w.z = pg8::cvt_pk_bf16(S[4], S[5]); w.w = pg8::cvt_pk_bf16(S[6], S[7]);
;         *(u32x4*)(KVB + (size_t)n * 16384) = w;
;         const float k8[8] = {lo_bf(kv[n].x), hi_bf(kv[n].x), lo_bf(kv[n].y), hi_bf(kv[n].y), lo_bf(kv[n].z), hi_bf(kv[n].z), lo_bf(kv[n].w), hi_bf(kv[n].w)};
; #pragma unroll
;         for (int x = 0; x < 8; ++x) S[x] = S[x] * c_dec + k8[x]; }
; __device__ __forceinline__ void sub_barrier(unsigned* cnt, const unsigned target, const int wv) {
;     ...
;         unsigned sp = 0u;
;         while (xb_ld(cnt) < target) { __builtin_amdgcn_s_sleep(2); if (++sp > (1u << 20)) break; }
;         __builtin_amdgcn_fence(__ATOMIC_ACQUIRE, "agent");
;         asm volatile("s_waitcnt vmcnt(0)" ::: "memory");
;     }
;     __syncthreads();
.LBB0_625:
	global_load_dword v1, v0, s[12:13] sc1
	s_mov_b64 s[18:19], -1
	s_waitcnt vmcnt(0)
	v_cmp_lt_u32_e32 vcc, s20, v1
	s_cbranch_vccnz .LBB0_624
	s_cmp_lg_u32 s21, 0
	s_sleep 2
	s_cbranch_scc0 .LBB0_623
	global_load_dword v1, v0, s[12:13] sc1
	s_waitcnt vmcnt(0)
	v_cmp_gt_u32_e32 vcc, s22, v1
	s_cbranch_vccz .LBB0_624
	s_sleep 2
	global_load_dword v1, v0, s[12:13] sc1
	s_waitcnt vmcnt(0)
	v_cmp_gt_u32_e32 vcc, s22, v1
	s_cbranch_vccz .LBB0_624
	s_sleep 2
	global_load_dword v1, v0, s[12:13] sc1
	s_waitcnt vmcnt(0)
	v_cmp_gt_u32_e32 vcc, s22, v1
	s_cbranch_vccz .LBB0_624
	s_sleep 2
	global_load_dword v1, v0, s[12:13] sc1
	s_waitcnt vmcnt(0)
	v_cmp_gt_u32_e32 vcc, s22, v1
	s_cbranch_vccz .LBB0_624
	s_sleep 2
	global_load_dword v1, v0, s[12:13] sc1
	s_waitcnt vmcnt(0)
	v_cmp_gt_u32_e32 vcc, s22, v1
	s_cbranch_vccz .LBB0_624
	s_sleep 2
	global_load_dword v1, v0, s[12:13] sc1
	s_waitcnt vmcnt(0)
	v_cmp_gt_u32_e32 vcc, s22, v1
	s_cbranch_vccz .LBB0_624
	s_sleep 2
	global_load_dword v1, v0, s[12:13] sc1
	s_waitcnt vmcnt(0)
	v_cmp_gt_u32_e32 vcc, s22, v1
	s_cbranch_vccz .LBB0_624
	s_sleep 2
	s_add_i32 s21, s21, -8
	s_mov_b64 s[18:19], 0
	s_branch .LBB0_624
.LBB0_635:
	s_waitcnt vmcnt(0)
.LBB0_636:
	s_or_b64 exec, exec, s[8:9]
	s_lshl_b32 s8, s49, 9
	s_add_i32 s8, s33, s8
	s_barrier
	v_mbcnt_lo_u32_b32 v66, -1, 0
	v_mbcnt_hi_u32_b32 v66, -1, v66
	v_mov_b32_e32 v4, 0xcb64800
	v_add_u32_e32 v47, s8, v66
	v_ashrrev_i32_e32 v44, 11, v47
	v_subrev_u32_e32 v0, 29, v44
	v_cmp_gt_i32_e32 vcc, 29, v44
	v_ashrrev_i32_e32 v45, 31, v44
	v_mov_b32_e32 v1, 0
	v_cndmask_b32_e32 v2, v0, v44, vcc
	v_mov_b32_e32 v0, 0x1444800
	v_cndmask_b32_e32 v3, 0, v45, vcc
	v_cndmask_b32_e32 v0, v0, v4, vcc
	v_and_b32_e32 v6, 3, v44
	v_lshl_add_u64 v[4:5], s[10:11], 0, v[0:1]
	v_lshlrev_b64 v[2:3], 19, v[2:3]
	v_lshl_add_u64 v[2:3], v[4:5], 0, v[2:3]
	v_cvt_f32_ubyte0_e32 v4, v6
	v_sub_f32_e32 v4, 0xc0a00000, v4
	s_mov_b32 s18, 0xc2fc0000
	v_mov_b32_e32 v5, 0x42800000
	v_cmp_gt_f32_e32 vcc, s18, v4
	v_not_b32_e32 v46, 63
	v_lshlrev_b32_e32 v0, 4, v47
	v_cndmask_b32_e32 v6, 0, v5, vcc
	v_add_f32_e32 v4, v4, v6
	v_exp_f32_e32 v4, v4
	v_cndmask_b32_e32 v6, 0, v46, vcc
	v_and_b32_e32 v0, 0x7ff0, v0
	s_mov_b32 s19, 0x800000
	v_ldexp_f32 v4, v4, v6
	v_sub_f32_e32 v4, 1.0, v4
	v_cmp_gt_f32_e32 vcc, s19, v4
	v_lshl_add_u64 v[92:93], v[2:3], 0, v[0:1]
	v_mov_b32_e32 v0, 0x42000000
	s_mov_b32 s19, 0x8000
	v_cndmask_b32_e64 v6, 0, 32, vcc
	v_cndmask_b32_e32 v0, 0, v0, vcc
	v_add_co_u32_e32 v94, vcc, s19, v92
	s_load_dwordx2 s[8:9], s[38:39], 0xd0
	s_nop 0
	v_addc_co_u32_e32 v95, vcc, 0, v93, vcc
	global_load_dwordx4 v[68:71], v[92:93], off
	global_load_dwordx4 v[72:75], v[94:95], off
	s_mov_b32 s19, 0x10000
	v_add_co_u32_e32 v96, vcc, s19, v92
	s_mov_b32 s19, 0x18000
	s_nop 0
	v_addc_co_u32_e32 v97, vcc, 0, v93, vcc
	v_add_co_u32_e32 v98, vcc, s19, v92
	s_mov_b32 s19, 0x20000
	s_nop 0
	v_addc_co_u32_e32 v99, vcc, 0, v93, vcc
	global_load_dwordx4 v[76:79], v[96:97], off
	global_load_dwordx4 v[80:83], v[98:99], off
	v_add_co_u32_e32 v100, vcc, s19, v92
	s_mov_b32 s19, 0x28000
	s_nop 0
	v_addc_co_u32_e32 v101, vcc, 0, v93, vcc
	v_add_co_u32_e32 v102, vcc, s19, v92
	s_mov_b32 s19, 0x30000
	s_nop 0
	v_addc_co_u32_e32 v103, vcc, 0, v93, vcc
	global_load_dwordx4 v[84:87], v[100:101], off
	global_load_dwordx4 v[88:91], v[102:103], off
	v_add_co_u32_e32 v104, vcc, s19, v92
	s_mov_b32 s19, 0x38000
	s_nop 0
	v_addc_co_u32_e32 v105, vcc, 0, v93, vcc
	v_add_co_u32_e32 v64, vcc, s19, v92
	s_mov_b32 s19, 0x40000
	s_nop 0
	v_addc_co_u32_e32 v65, vcc, 0, v93, vcc
	global_load_dwordx4 v[40:43], v[104:105], off
	global_load_dwordx4 v[36:39], v[64:65], off
	v_add_co_u32_e32 v62, vcc, s19, v92
	s_mov_b32 s19, 0x48000
	s_nop 0
	v_addc_co_u32_e32 v63, vcc, 0, v93, vcc
	v_add_co_u32_e32 v60, vcc, s19, v92
	s_mov_b32 s19, 0x50000
	s_nop 0
	v_addc_co_u32_e32 v61, vcc, 0, v93, vcc
	global_load_dwordx4 v[32:35], v[62:63], off
	global_load_dwordx4 v[28:31], v[60:61], off
	v_add_co_u32_e32 v58, vcc, s19, v92
	s_mov_b32 s19, 0x58000
	s_nop 0
	v_addc_co_u32_e32 v59, vcc, 0, v93, vcc
	v_add_co_u32_e32 v56, vcc, s19, v92
	s_mov_b32 s19, 0x60000
	s_nop 0
	v_addc_co_u32_e32 v57, vcc, 0, v93, vcc
	global_load_dwordx4 v[24:27], v[58:59], off
	global_load_dwordx4 v[20:23], v[56:57], off
	v_add_co_u32_e32 v54, vcc, s19, v92
	s_mov_b32 s19, 0x68000
	s_nop 0
	v_addc_co_u32_e32 v55, vcc, 0, v93, vcc
	v_ldexp_f32 v4, v4, v6
	v_add_co_u32_e32 v52, vcc, s19, v92
	v_log_f32_e32 v4, v4
	s_nop 0
	v_addc_co_u32_e32 v53, vcc, 0, v93, vcc
	global_load_dwordx4 v[16:19], v[54:55], off
	global_load_dwordx4 v[12:15], v[52:53], off
	s_mov_b32 s19, 0x70000
	v_add_co_u32_e32 v50, vcc, s19, v92
	s_mov_b32 s19, 0x78000
	s_nop 0
	v_addc_co_u32_e32 v51, vcc, 0, v93, vcc
	v_sub_f32_e32 v0, v4, v0
	v_add_co_u32_e32 v48, vcc, s19, v92
	v_mul_f32_e32 v2, 0x43000000, v0
	s_nop 0
	v_addc_co_u32_e32 v49, vcc, 0, v93, vcc
	v_cmp_gt_f32_e32 vcc, s18, v2
	v_mov_b32_e32 v3, v1
	s_mov_b32 s18, 0x4308000
	v_cndmask_b32_e32 v2, 0, v5, vcc
	v_fmac_f32_e32 v2, 0x43000000, v0
	v_exp_f32_e32 v0, v2
	global_load_dwordx4 v[8:11], v[50:51], off
	global_load_dwordx4 v[4:7], v[48:49], off
	v_cndmask_b32_e32 v2, 0, v46, vcc
	v_ldexp_f32 v46, v0, v2
	v_mov_b32_e32 v0, v1
	v_mov_b32_e32 v2, v1
	global_store_dwordx4 v[92:93], v[0:3], off
	s_nop 1
	v_mul_f32_e32 v0, 0, v46
	s_waitcnt vmcnt(16)
; __device__ __forceinline__ unsigned cvt_pk_bf16(float lo, float hi) { const f32x2_t v = {lo, hi}; const bf16x2_t b = __builtin_convertvector(v, bf16x2_t); return __builtin_bit_cast(unsigned, b); }
; __device__ __forceinline__ float lo_bf(unsigned x) { return __uint_as_float(x << 16); }
; __device__ __forceinline__ float hi_bf(unsigned x) { return __uint_as_float(x & 0xffff0000u); }
; __device__ __forceinline__ void ret_prefix(PR P, const int item) {
;     ...
; #pragma unroll
;     for (int n = 0; n < 16; ++n) { u32x4 w; w.x = pg8::cvt_pk_bf16(S[0], S[1]); w.y = pg8::cvt_pk_bf16(S[2], S[3]); w.z = pg8::cvt_pk_bf16(S[4], S[5]); w.w = pg8::cvt_pk_bf16(S[6], S[7]);
;         *(u32x4*)(KVB + (size_t)n * 16384) = w;
;         const float k8[8] = {lo_bf(kv[n].x), hi_bf(kv[n].x), lo_bf(kv[n].y), hi_bf(kv[n].y), lo_bf(kv[n].z), hi_bf(kv[n].z), lo_bf(kv[n].w), hi_bf(kv[n].w)};
; #pragma unroll
;         for (int x = 0; x < 8; ++x) S[x] = S[x] * c_dec + k8[x]; }
	v_lshlrev_b32_e32 v2, 16, v68
	v_and_b32_e32 v3, 0xffff0000, v68
	v_lshlrev_b32_e32 v68, 16, v69
	v_and_b32_e32 v69, 0xffff0000, v69
	v_pk_add_f32 v[92:93], v[0:1], v[68:69] op_sel_hi:[0,1]
	v_lshlrev_b32_e32 v68, 16, v70
	v_and_b32_e32 v69, 0xffff0000, v70
	v_pk_add_f32 v[106:107], v[0:1], v[68:69] op_sel_hi:[0,1]
	v_lshlrev_b32_e32 v68, 16, v71
	v_and_b32_e32 v69, 0xffff0000, v71
	v_pk_add_f32 v[2:3], v[0:1], v[2:3] op_sel_hi:[0,1]
	v_pk_add_f32 v[108:109], v[0:1], v[68:69] op_sel_hi:[0,1]
	v_cvt_pk_bf16_f32 v68, v2, v3
	v_cvt_pk_bf16_f32 v69, v92, v93
	v_cvt_pk_bf16_f32 v70, v106, v107
	v_cvt_pk_bf16_f32 v71, v108, v109
	global_store_dwordx4 v[94:95], v[68:71], off
	v_lshlrev_b32_e32 v0, 12, v66
	v_and_b32_e32 v0, 0xf000, v0
	s_waitcnt vmcnt(16)
	v_lshlrev_b32_e32 v68, 16, v72
	v_and_b32_e32 v69, 0xffff0000, v72
	v_pk_fma_f32 v[2:3], v[46:47], v[2:3], v[68:69] op_sel_hi:[0,1,1]
	v_lshlrev_b32_e32 v68, 16, v73
	v_and_b32_e32 v69, 0xffff0000, v73
	v_pk_fma_f32 v[72:73], v[46:47], v[92:93], v[68:69] op_sel_hi:[0,1,1]
	v_lshlrev_b32_e32 v68, 16, v74
	v_and_b32_e32 v69, 0xffff0000, v74
	v_pk_fma_f32 v[92:93], v[46:47], v[106:107], v[68:69] op_sel_hi:[0,1,1]
	v_lshlrev_b32_e32 v68, 16, v75
	v_and_b32_e32 v69, 0xffff0000, v75
	v_pk_fma_f32 v[74:75], v[46:47], v[108:109], v[68:69] op_sel_hi:[0,1,1]
	v_cvt_pk_bf16_f32 v68, v2, v3
	v_cvt_pk_bf16_f32 v69, v72, v73
	v_cvt_pk_bf16_f32 v70, v92, v93
	v_cvt_pk_bf16_f32 v71, v74, v75
	global_store_dwordx4 v[96:97], v[68:71], off
	s_waitcnt vmcnt(16)
	s_nop 0
	v_lshlrev_b32_e32 v68, 16, v76
	v_and_b32_e32 v69, 0xffff0000, v76
	v_pk_fma_f32 v[2:3], v[46:47], v[2:3], v[68:69] op_sel_hi:[0,1,1]
	v_lshlrev_b32_e32 v68, 16, v77
	v_and_b32_e32 v69, 0xffff0000, v77
	v_pk_fma_f32 v[72:73], v[46:47], v[72:73], v[68:69] op_sel_hi:[0,1,1]
	v_lshlrev_b32_e32 v68, 16, v78
	v_and_b32_e32 v69, 0xffff0000, v78
	v_pk_fma_f32 v[76:77], v[46:47], v[92:93], v[68:69] op_sel_hi:[0,1,1]
	v_lshlrev_b32_e32 v68, 16, v79
	v_and_b32_e32 v69, 0xffff0000, v79
	v_pk_fma_f32 v[74:75], v[46:47], v[74:75], v[68:69] op_sel_hi:[0,1,1]
	v_cvt_pk_bf16_f32 v68, v2, v3
	v_cvt_pk_bf16_f32 v69, v72, v73
	v_cvt_pk_bf16_f32 v70, v76, v77
	v_cvt_pk_bf16_f32 v71, v74, v75
	global_store_dwordx4 v[98:99], v[68:71], off
	s_waitcnt vmcnt(16)
	s_nop 0
	v_lshlrev_b32_e32 v68, 16, v80
	v_and_b32_e32 v69, 0xffff0000, v80
	v_pk_fma_f32 v[2:3], v[46:47], v[2:3], v[68:69] op_sel_hi:[0,1,1]
	v_lshlrev_b32_e32 v68, 16, v81
	v_and_b32_e32 v69, 0xffff0000, v81
	v_pk_fma_f32 v[72:73], v[46:47], v[72:73], v[68:69] op_sel_hi:[0,1,1]
	v_lshlrev_b32_e32 v68, 16, v82
	v_and_b32_e32 v69, 0xffff0000, v82
	v_pk_fma_f32 v[76:77], v[46:47], v[76:77], v[68:69] op_sel_hi:[0,1,1]
	v_lshlrev_b32_e32 v68, 16, v83
	v_and_b32_e32 v69, 0xffff0000, v83
	v_pk_fma_f32 v[74:75], v[46:47], v[74:75], v[68:69] op_sel_hi:[0,1,1]
	v_cvt_pk_bf16_f32 v68, v2, v3
	v_cvt_pk_bf16_f32 v69, v72, v73
	v_cvt_pk_bf16_f32 v70, v76, v77
	v_cvt_pk_bf16_f32 v71, v74, v75
	global_store_dwordx4 v[100:101], v[68:71], off
	s_waitcnt vmcnt(16)
	s_nop 0
	v_lshlrev_b32_e32 v68, 16, v84
	v_and_b32_e32 v69, 0xffff0000, v84
	v_pk_fma_f32 v[2:3], v[46:47], v[2:3], v[68:69] op_sel_hi:[0,1,1]
	v_lshlrev_b32_e32 v68, 16, v85
	v_and_b32_e32 v69, 0xffff0000, v85
	v_pk_fma_f32 v[72:73], v[46:47], v[72:73], v[68:69] op_sel_hi:[0,1,1]
	v_lshlrev_b32_e32 v68, 16, v86
	v_and_b32_e32 v69, 0xffff0000, v86
	v_pk_fma_f32 v[76:77], v[46:47], v[76:77], v[68:69] op_sel_hi:[0,1,1]
	v_lshlrev_b32_e32 v68, 16, v87
	v_and_b32_e32 v69, 0xffff0000, v87
	v_pk_fma_f32 v[74:75], v[46:47], v[74:75], v[68:69] op_sel_hi:[0,1,1]
	v_cvt_pk_bf16_f32 v68, v2, v3
	v_cvt_pk_bf16_f32 v69, v72, v73
	v_cvt_pk_bf16_f32 v70, v76, v77
	v_cvt_pk_bf16_f32 v71, v74, v75
	global_store_dwordx4 v[102:103], v[68:71], off
	s_waitcnt vmcnt(16)
	s_nop 0
	v_lshlrev_b32_e32 v68, 16, v88
	v_and_b32_e32 v69, 0xffff0000, v88
	v_pk_fma_f32 v[2:3], v[46:47], v[2:3], v[68:69] op_sel_hi:[0,1,1]
	v_lshlrev_b32_e32 v68, 16, v89
	v_and_b32_e32 v69, 0xffff0000, v89
	v_pk_fma_f32 v[72:73], v[46:47], v[72:73], v[68:69] op_sel_hi:[0,1,1]
	v_lshlrev_b32_e32 v68, 16, v90
	v_and_b32_e32 v69, 0xffff0000, v90
	v_pk_fma_f32 v[76:77], v[46:47], v[76:77], v[68:69] op_sel_hi:[0,1,1]
	v_lshlrev_b32_e32 v68, 16, v91
	v_and_b32_e32 v69, 0xffff0000, v91
	v_pk_fma_f32 v[74:75], v[46:47], v[74:75], v[68:69] op_sel_hi:[0,1,1]
	v_cvt_pk_bf16_f32 v68, v2, v3
	v_cvt_pk_bf16_f32 v69, v72, v73
	v_cvt_pk_bf16_f32 v70, v76, v77
	v_cvt_pk_bf16_f32 v71, v74, v75
	global_store_dwordx4 v[104:105], v[68:71], off
	s_waitcnt vmcnt(16)
	s_nop 0
	v_lshlrev_b32_e32 v68, 16, v40
	v_and_b32_e32 v69, 0xffff0000, v40
	v_lshlrev_b32_e32 v40, 16, v41
	v_and_b32_e32 v41, 0xffff0000, v41
	v_pk_fma_f32 v[2:3], v[46:47], v[2:3], v[68:69] op_sel_hi:[0,1,1]
	v_pk_fma_f32 v[68:69], v[46:47], v[72:73], v[40:41] op_sel_hi:[0,1,1]
	v_lshlrev_b32_e32 v40, 16, v42
	v_and_b32_e32 v41, 0xffff0000, v42
	v_pk_fma_f32 v[70:71], v[46:47], v[76:77], v[40:41] op_sel_hi:[0,1,1]
	v_lshlrev_b32_e32 v40, 16, v43
	v_and_b32_e32 v41, 0xffff0000, v43
	v_pk_fma_f32 v[72:73], v[46:47], v[74:75], v[40:41] op_sel_hi:[0,1,1]
	v_cvt_pk_bf16_f32 v40, v2, v3
	v_cvt_pk_bf16_f32 v41, v68, v69
	v_cvt_pk_bf16_f32 v42, v70, v71
	v_cvt_pk_bf16_f32 v43, v72, v73
	global_store_dwordx4 v[64:65], v[40:43], off
	s_waitcnt vmcnt(16)
; __device__ __forceinline__ unsigned cvt_pk_bf16(float lo, float hi) { const f32x2_t v = {lo, hi}; const bf16x2_t b = __builtin_convertvector(v, bf16x2_t); return __builtin_bit_cast(unsigned, b); }
; __device__ __forceinline__ float lo_bf(unsigned x) { return __uint_as_float(x << 16); }
; __device__ __forceinline__ float hi_bf(unsigned x) { return __uint_as_float(x & 0xffff0000u); }
; __device__ __forceinline__ void ret_prefix(PR P, const int item) {
;     ...
; #pragma unroll
;     for (int n = 0; n < 16; ++n) { u32x4 w; w.x = pg8::cvt_pk_bf16(S[0], S[1]); w.y = pg8::cvt_pk_bf16(S[2], S[3]); w.z = pg8::cvt_pk_bf16(S[4], S[5]); w.w = pg8::cvt_pk_bf16(S[6], S[7]);
;         *(u32x4*)(KVB + (size_t)n * 16384) = w;
;         const float k8[8] = {lo_bf(kv[n].x), hi_bf(kv[n].x), lo_bf(kv[n].y), hi_bf(kv[n].y), lo_bf(kv[n].z), hi_bf(kv[n].z), lo_bf(kv[n].w), hi_bf(kv[n].w)};
; #pragma unroll
;         for (int x = 0; x < 8; ++x) S[x] = S[x] * c_dec + k8[x]; }
	s_nop 0
	v_lshlrev_b32_e32 v40, 16, v36
	v_and_b32_e32 v41, 0xffff0000, v36
	v_lshlrev_b32_e32 v36, 16, v37
	v_and_b32_e32 v37, 0xffff0000, v37
	v_pk_fma_f32 v[2:3], v[46:47], v[2:3], v[40:41] op_sel_hi:[0,1,1]
	v_pk_fma_f32 v[40:41], v[46:47], v[68:69], v[36:37] op_sel_hi:[0,1,1]
	v_lshlrev_b32_e32 v36, 16, v38
	v_and_b32_e32 v37, 0xffff0000, v38
	v_pk_fma_f32 v[42:43], v[46:47], v[70:71], v[36:37] op_sel_hi:[0,1,1]
	v_lshlrev_b32_e32 v36, 16, v39
	v_and_b32_e32 v37, 0xffff0000, v39
	v_pk_fma_f32 v[64:65], v[46:47], v[72:73], v[36:37] op_sel_hi:[0,1,1]
	v_cvt_pk_bf16_f32 v36, v2, v3
	v_cvt_pk_bf16_f32 v37, v40, v41
	v_cvt_pk_bf16_f32 v38, v42, v43
	v_cvt_pk_bf16_f32 v39, v64, v65
	global_store_dwordx4 v[62:63], v[36:39], off
	s_waitcnt vmcnt(16)
	s_nop 0
	v_lshlrev_b32_e32 v36, 16, v32
	v_and_b32_e32 v37, 0xffff0000, v32
	v_lshlrev_b32_e32 v32, 16, v33
	v_and_b32_e32 v33, 0xffff0000, v33
	v_pk_fma_f32 v[2:3], v[46:47], v[2:3], v[36:37] op_sel_hi:[0,1,1]
	v_pk_fma_f32 v[36:37], v[46:47], v[40:41], v[32:33] op_sel_hi:[0,1,1]
	v_lshlrev_b32_e32 v32, 16, v34
	v_and_b32_e32 v33, 0xffff0000, v34
	v_pk_fma_f32 v[38:39], v[46:47], v[42:43], v[32:33] op_sel_hi:[0,1,1]
	v_lshlrev_b32_e32 v32, 16, v35
	v_and_b32_e32 v33, 0xffff0000, v35
	v_pk_fma_f32 v[40:41], v[46:47], v[64:65], v[32:33] op_sel_hi:[0,1,1]
	v_cvt_pk_bf16_f32 v32, v2, v3
	v_cvt_pk_bf16_f32 v33, v36, v37
	v_cvt_pk_bf16_f32 v34, v38, v39
	v_cvt_pk_bf16_f32 v35, v40, v41
	global_store_dwordx4 v[60:61], v[32:35], off
	s_waitcnt vmcnt(16)
	s_nop 0
	v_lshlrev_b32_e32 v32, 16, v28
	v_and_b32_e32 v33, 0xffff0000, v28
	v_lshlrev_b32_e32 v28, 16, v29
	v_and_b32_e32 v29, 0xffff0000, v29
	v_pk_fma_f32 v[2:3], v[46:47], v[2:3], v[32:33] op_sel_hi:[0,1,1]
	v_pk_fma_f32 v[32:33], v[46:47], v[36:37], v[28:29] op_sel_hi:[0,1,1]
	v_lshlrev_b32_e32 v28, 16, v30
	v_and_b32_e32 v29, 0xffff0000, v30
	v_pk_fma_f32 v[34:35], v[46:47], v[38:39], v[28:29] op_sel_hi:[0,1,1]
	v_lshlrev_b32_e32 v28, 16, v31
	v_and_b32_e32 v29, 0xffff0000, v31
	v_pk_fma_f32 v[36:37], v[46:47], v[40:41], v[28:29] op_sel_hi:[0,1,1]
	v_cvt_pk_bf16_f32 v28, v2, v3
	v_cvt_pk_bf16_f32 v29, v32, v33
	v_cvt_pk_bf16_f32 v30, v34, v35
	v_cvt_pk_bf16_f32 v31, v36, v37
	global_store_dwordx4 v[58:59], v[28:31], off
	s_waitcnt vmcnt(16)
	s_nop 0
	v_lshlrev_b32_e32 v28, 16, v24
	v_and_b32_e32 v29, 0xffff0000, v24
	v_lshlrev_b32_e32 v24, 16, v25
	v_and_b32_e32 v25, 0xffff0000, v25
	v_pk_fma_f32 v[2:3], v[46:47], v[2:3], v[28:29] op_sel_hi:[0,1,1]
	v_pk_fma_f32 v[28:29], v[46:47], v[32:33], v[24:25] op_sel_hi:[0,1,1]
	v_lshlrev_b32_e32 v24, 16, v26
	v_and_b32_e32 v25, 0xffff0000, v26
	v_pk_fma_f32 v[30:31], v[46:47], v[34:35], v[24:25] op_sel_hi:[0,1,1]
	v_lshlrev_b32_e32 v24, 16, v27
	v_and_b32_e32 v25, 0xffff0000, v27
	v_pk_fma_f32 v[32:33], v[46:47], v[36:37], v[24:25] op_sel_hi:[0,1,1]
	v_cvt_pk_bf16_f32 v24, v2, v3
	v_cvt_pk_bf16_f32 v25, v28, v29
	v_cvt_pk_bf16_f32 v26, v30, v31
	v_cvt_pk_bf16_f32 v27, v32, v33
	global_store_dwordx4 v[56:57], v[24:27], off
	s_waitcnt vmcnt(16)
	s_nop 0
	v_lshlrev_b32_e32 v24, 16, v20
	v_and_b32_e32 v25, 0xffff0000, v20
	v_lshlrev_b32_e32 v20, 16, v21
	v_and_b32_e32 v21, 0xffff0000, v21
	v_pk_fma_f32 v[2:3], v[46:47], v[2:3], v[24:25] op_sel_hi:[0,1,1]
	v_pk_fma_f32 v[24:25], v[46:47], v[28:29], v[20:21] op_sel_hi:[0,1,1]
	v_lshlrev_b32_e32 v20, 16, v22
	v_and_b32_e32 v21, 0xffff0000, v22
	v_pk_fma_f32 v[26:27], v[46:47], v[30:31], v[20:21] op_sel_hi:[0,1,1]
	v_lshlrev_b32_e32 v20, 16, v23
	v_and_b32_e32 v21, 0xffff0000, v23
	v_pk_fma_f32 v[28:29], v[46:47], v[32:33], v[20:21] op_sel_hi:[0,1,1]
	v_cvt_pk_bf16_f32 v20, v2, v3
	v_cvt_pk_bf16_f32 v21, v24, v25
	v_cvt_pk_bf16_f32 v22, v26, v27
	v_cvt_pk_bf16_f32 v23, v28, v29
	global_store_dwordx4 v[54:55], v[20:23], off
	s_waitcnt vmcnt(16)
; __device__ __forceinline__ int fresh_tid(int wv) { int l; asm volatile("v_mbcnt_lo_u32_b32 %0, -1, 0\n\tv_mbcnt_hi_u32_b32 %0, -1, %0" : "=v"(l)); return wv * 64 + l; }
; __device__ __forceinline__ unsigned cvt_pk_bf16(float lo, float hi) { const f32x2_t v = {lo, hi}; const bf16x2_t b = __builtin_convertvector(v, bf16x2_t); return __builtin_bit_cast(unsigned, b); }
; __device__ __forceinline__ float lo_bf(unsigned x) { return __uint_as_float(x << 16); }
; __device__ __forceinline__ float hi_bf(unsigned x) { return __uint_as_float(x & 0xffff0000u); }
; __device__ __forceinline__ unsigned xb_add(unsigned* p, unsigned v) { return __hip_atomic_fetch_add(p, v, __ATOMIC_RELAXED, __HIP_MEMORY_SCOPE_AGENT); }
; __device__ __forceinline__ void ret_prefix(PR P, const int item) {
;     ...
; #pragma unroll
;     for (int n = 0; n < 16; ++n) { u32x4 w; w.x = pg8::cvt_pk_bf16(S[0], S[1]); w.y = pg8::cvt_pk_bf16(S[2], S[3]); w.z = pg8::cvt_pk_bf16(S[4], S[5]); w.w = pg8::cvt_pk_bf16(S[6], S[7]);
;         *(u32x4*)(KVB + (size_t)n * 16384) = w;
;         const float k8[8] = {lo_bf(kv[n].x), hi_bf(kv[n].x), lo_bf(kv[n].y), hi_bf(kv[n].y), lo_bf(kv[n].z), hi_bf(kv[n].z), lo_bf(kv[n].w), hi_bf(kv[n].w)};
; #pragma unroll
;         for (int x = 0; x < 8; ++x) S[x] = S[x] * c_dec + k8[x]; }
;     const int e = i8 >> 7, d0 = i8 & 127;
; #pragma unroll
;     for (int x = 0; x < 8; ++x) P.out[O_RTP + ((size_t)bh * 128 + d0 + x) * 128 + e] = S[x];
; __device__ __forceinline__ void sub_barrier(unsigned* cnt, const unsigned target, const int wv) {
;     asm volatile("s_waitcnt vmcnt(0)" ::: "memory");
;     __syncthreads();
;     if (fresh_tid(wv) == 0) {
;         __builtin_amdgcn_fence(__ATOMIC_RELEASE, "agent");
;         asm volatile("s_waitcnt vmcnt(0)" ::: "memory");
;         (void)xb_add(cnt, 1u);
	s_nop 0
	v_lshlrev_b32_e32 v20, 16, v16
	v_and_b32_e32 v21, 0xffff0000, v16
	v_lshlrev_b32_e32 v16, 16, v17
	v_and_b32_e32 v17, 0xffff0000, v17
	v_pk_fma_f32 v[2:3], v[46:47], v[2:3], v[20:21] op_sel_hi:[0,1,1]
	v_pk_fma_f32 v[20:21], v[46:47], v[24:25], v[16:17] op_sel_hi:[0,1,1]
	v_lshlrev_b32_e32 v16, 16, v18
	v_and_b32_e32 v17, 0xffff0000, v18
	v_pk_fma_f32 v[22:23], v[46:47], v[26:27], v[16:17] op_sel_hi:[0,1,1]
	v_lshlrev_b32_e32 v16, 16, v19
	v_and_b32_e32 v17, 0xffff0000, v19
	v_pk_fma_f32 v[24:25], v[46:47], v[28:29], v[16:17] op_sel_hi:[0,1,1]
	v_cvt_pk_bf16_f32 v16, v2, v3
	v_cvt_pk_bf16_f32 v17, v20, v21
	v_cvt_pk_bf16_f32 v18, v22, v23
	v_cvt_pk_bf16_f32 v19, v24, v25
	global_store_dwordx4 v[52:53], v[16:19], off
	s_waitcnt vmcnt(16)
	s_nop 0
	v_lshlrev_b32_e32 v16, 16, v12
	v_and_b32_e32 v17, 0xffff0000, v12
	v_lshlrev_b32_e32 v12, 16, v13
	v_and_b32_e32 v13, 0xffff0000, v13
	v_pk_fma_f32 v[2:3], v[46:47], v[2:3], v[16:17] op_sel_hi:[0,1,1]
	v_pk_fma_f32 v[16:17], v[46:47], v[20:21], v[12:13] op_sel_hi:[0,1,1]
	v_lshlrev_b32_e32 v12, 16, v14
	v_and_b32_e32 v13, 0xffff0000, v14
	v_pk_fma_f32 v[18:19], v[46:47], v[22:23], v[12:13] op_sel_hi:[0,1,1]
	v_lshlrev_b32_e32 v12, 16, v15
	v_and_b32_e32 v13, 0xffff0000, v15
	v_pk_fma_f32 v[20:21], v[46:47], v[24:25], v[12:13] op_sel_hi:[0,1,1]
	v_cvt_pk_bf16_f32 v12, v2, v3
	v_cvt_pk_bf16_f32 v13, v16, v17
	v_cvt_pk_bf16_f32 v14, v18, v19
	v_cvt_pk_bf16_f32 v15, v20, v21
	global_store_dwordx4 v[50:51], v[12:15], off
	s_waitcnt vmcnt(16)
	s_nop 0
	v_lshlrev_b32_e32 v12, 16, v8
	v_and_b32_e32 v13, 0xffff0000, v8
	v_lshlrev_b32_e32 v8, 16, v9
	v_and_b32_e32 v9, 0xffff0000, v9
	v_pk_fma_f32 v[2:3], v[46:47], v[2:3], v[12:13] op_sel_hi:[0,1,1]
	v_pk_fma_f32 v[12:13], v[46:47], v[16:17], v[8:9] op_sel_hi:[0,1,1]
	v_lshlrev_b32_e32 v8, 16, v10
	v_and_b32_e32 v9, 0xffff0000, v10
	v_pk_fma_f32 v[14:15], v[46:47], v[18:19], v[8:9] op_sel_hi:[0,1,1]
	v_lshlrev_b32_e32 v8, 16, v11
	v_and_b32_e32 v9, 0xffff0000, v11
	v_pk_fma_f32 v[16:17], v[46:47], v[20:21], v[8:9] op_sel_hi:[0,1,1]
	v_cvt_pk_bf16_f32 v8, v2, v3
	v_cvt_pk_bf16_f32 v9, v12, v13
	v_cvt_pk_bf16_f32 v10, v14, v15
	v_cvt_pk_bf16_f32 v11, v16, v17
	global_store_dwordx4 v[48:49], v[8:11], off
	s_waitcnt vmcnt(16)
	s_nop 0
	v_lshlrev_b32_e32 v8, 16, v4
	v_and_b32_e32 v4, 0xffff0000, v4
	v_fmac_f32_e32 v8, v46, v2
	v_fmac_f32_e32 v4, v46, v3
	v_lshlrev_b64 v[2:3], 16, v[44:45]
	s_waitcnt lgkmcnt(0)
	v_lshl_add_u64 v[2:3], s[8:9], 0, v[2:3]
	v_lshl_add_u64 v[2:3], v[2:3], 0, v[0:1]
	v_lshrrev_b32_e32 v0, 2, v47
	v_and_b32_e32 v0, 0x1fc, v0
	v_lshl_add_u64 v[0:1], v[2:3], 0, v[0:1]
	v_add_co_u32_e32 v0, vcc, s18, v0
	v_lshlrev_b32_e32 v9, 16, v5
	v_and_b32_e32 v5, 0xffff0000, v5
	v_lshlrev_b32_e32 v10, 16, v6
	v_and_b32_e32 v6, 0xffff0000, v6
	v_lshlrev_b32_e32 v11, 16, v7
	v_and_b32_e32 v7, 0xffff0000, v7
	v_addc_co_u32_e32 v1, vcc, 0, v1, vcc
	v_fmac_f32_e32 v9, v46, v12
	v_fmac_f32_e32 v5, v46, v13
	v_fmac_f32_e32 v10, v46, v14
	v_fmac_f32_e32 v6, v46, v15
	v_fmac_f32_e32 v11, v46, v16
	v_fmac_f32_e32 v7, v46, v17
	global_store_dword v[0:1], v8, off
	global_store_dword v[0:1], v4, off offset:512
	global_store_dword v[0:1], v9, off offset:1024
	global_store_dword v[0:1], v5, off offset:1536
	global_store_dword v[0:1], v10, off offset:2048
	global_store_dword v[0:1], v6, off offset:2560
	global_store_dword v[0:1], v11, off offset:3072
	global_store_dword v[0:1], v7, off offset:3584
	s_waitcnt vmcnt(0)
	s_barrier
	v_mbcnt_lo_u32_b32 v0, -1, 0
	v_mbcnt_hi_u32_b32 v0, -1, v0
	s_nop 0
	v_cmp_eq_u32_e32 vcc, s74, v0
	s_and_saveexec_b64 s[18:19], vcc
	s_cbranch_execz .LBB0_653
	s_mov_b64 s[20:21], exec
	buffer_wbl2 sc1
	buffer_inv sc1
	s_waitcnt vmcnt(0)
	s_waitcnt vmcnt(0)
	v_mbcnt_lo_u32_b32 v0, s20, 0
	v_mbcnt_hi_u32_b32 v0, s21, v0
	v_cmp_eq_u32_e32 vcc, 0, v0
	s_and_saveexec_b64 s[22:23], vcc
	s_cbranch_execz .LBB0_639
	s_bcnt1_i32_b64 s20, s[20:21]
	v_mov_b32_e32 v0, 0
	v_mov_b32_e32 v1, s20
	global_atomic_add v0, v1, s[12:13]

; __device__ __forceinline__ int fresh_tid(int wv) { int l; asm volatile("v_mbcnt_lo_u32_b32 %0, -1, 0\n\tv_mbcnt_hi_u32_b32 %0, -1, %0" : "=v"(l)); return wv * 64 + l; }
; #define LAS __attribute__((address_space(3)))
; __device__ __forceinline__ unsigned xb_ld(unsigned* p)              { return __hip_atomic_load(p, __ATOMIC_RELAXED, __HIP_MEMORY_SCOPE_AGENT); }
; __device__ __forceinline__ bf16_t* kvb_ptr(unsigned char* ws, int bh) { return (bf16_t*)(bh < 29 ? ws + WS_LA + (size_t)bh * 524288 : ws + WS_WIN + 17301504 + (size_t)(bh - 29) * 524288); }
; __device__ __forceinline__ void ret_unit_c(PR P, LAS unsigned char* lds, const int bh, const int n, const int wv) {
;     LAS bf16_t* QP = (LAS bf16_t*)lds; LAS bf16_t* ST = QP + 3 * BUFE; LAS float* YST = (LAS float*)(QP + BUFE);
;     const int tid = fresh_tid(wv), lane = tid & 63, wid = tid >> 6, wr = wid >> 1, wc = wid & 1, fr = lane & 15, fq = lane >> 4;
;     const int b = bh >> 2, h = bh & 3;
;     const bf16_t* PS = (const bf16_t*)(P.ws + WS_BIG); bf16_t* Y = (bf16_t*)(P.ws + WS_XN); const bf16_t* KVB = kvb_ptr(P.ws, bh) + (size_t)n * 16384;
;     const float lg2 = log2f(1.0f - exp2f(-5.0f - (float)h));
;     const int row0 = b * 2048 + n * 128;
;     unsigned kth[4][4];
;     ret_load_qk<false>(P, QP, QP, kth, tid, row0, n, h, 0.f, 0.f);
; __device__ __forceinline__ void sub_barrier(unsigned* cnt, const unsigned target, const int wv) {
;     ...
;         unsigned sp = 0u;
;         while (xb_ld(cnt) < target) { __builtin_amdgcn_s_sleep(2); if (++sp > (1u << 20)) break; }
;         __builtin_amdgcn_fence(__ATOMIC_ACQUIRE, "agent");
;         asm volatile("s_waitcnt vmcnt(0)" ::: "memory");
;     }
;     __syncthreads();
.LBB0_642:
	global_load_dword v1, v0, s[12:13] sc1
	s_mov_b64 s[20:21], -1
	s_waitcnt vmcnt(0)
	v_cmp_lt_u32_e32 vcc, s22, v1
	s_cbranch_vccnz .LBB0_641
	s_cmp_lg_u32 s23, 0
	s_sleep 2
	s_cbranch_scc0 .LBB0_640
	global_load_dword v1, v0, s[12:13] sc1
	s_waitcnt vmcnt(0)
	v_cmp_gt_u32_e32 vcc, s24, v1
	s_cbranch_vccz .LBB0_641
	s_sleep 2
	global_load_dword v1, v0, s[12:13] sc1
	s_waitcnt vmcnt(0)
	v_cmp_gt_u32_e32 vcc, s24, v1
	s_cbranch_vccz .LBB0_641
	s_sleep 2
	global_load_dword v1, v0, s[12:13] sc1
	s_waitcnt vmcnt(0)
	v_cmp_gt_u32_e32 vcc, s24, v1
	s_cbranch_vccz .LBB0_641
	s_sleep 2
	global_load_dword v1, v0, s[12:13] sc1
	s_waitcnt vmcnt(0)
	v_cmp_gt_u32_e32 vcc, s24, v1
	s_cbranch_vccz .LBB0_641
	s_sleep 2
	global_load_dword v1, v0, s[12:13] sc1
	s_waitcnt vmcnt(0)
	v_cmp_gt_u32_e32 vcc, s24, v1
	s_cbranch_vccz .LBB0_641
	s_sleep 2
	global_load_dword v1, v0, s[12:13] sc1
	s_waitcnt vmcnt(0)
	v_cmp_gt_u32_e32 vcc, s24, v1
	s_cbranch_vccz .LBB0_641
	s_sleep 2
	global_load_dword v1, v0, s[12:13] sc1
	s_waitcnt vmcnt(0)
	v_cmp_gt_u32_e32 vcc, s24, v1
	s_cbranch_vccz .LBB0_641
	s_sleep 2
	s_add_i32 s23, s23, -8
	s_mov_b64 s[20:21], 0
	s_branch .LBB0_641
.LBB0_652:
	s_waitcnt vmcnt(0)
.LBB0_653:
	s_or_b64 exec, exec, s[18:19]
	s_barrier
	s_load_dwordx2 s[12:13], s[38:39], 0xa8
	s_movk_i32 s28, 0xff80
	s_mov_b32 s19, 0
	s_mov_b32 s29, 0xcb64800
	s_mov_b32 s30, 0xc2fc0000
	v_mov_b32_e32 v62, 0x42800000
	v_mov_b32_e32 v29, 0
	s_movk_i32 s31, 0x1e00
	v_mov_b64_e32 v[30:31], s[10:11]
	s_mov_b64 s[20:21], 0x3d45600
	s_mov_b32 s34, 0x3d45000
	s_movk_i32 s35, 0x110
	s_add_i32 s36, 0, 0x19800
	s_mov_b32 s37, 0x800000
	v_mov_b32_e32 v63, 0x42000000
	v_not_b32_e32 v64, 63
	s_movk_i32 s40, 0x210
	s_mov_b64 s[22:23], 0x1bc4c00
	s_mov_b32 s41, 0x1bc4000
	s_movk_i32 s42, 0x1600
	s_mov_b64 s[24:25], 0x3d46200
	s_mov_b32 s43, 0x3d46000
	v_mov_b32_e32 v65, 0x3727c5ac
